# attn_d v2 (max folded into MFMA C, deferred rescale) + natten: removed barriers around wave-private V staging
# speedup vs baseline: 1.0692x; 1.0078x over previous
.LBB0_526:
	s_or_b64 exec, exec, s[4:5]
	v_max3_f32 v4, v68, s29, v67
	v_max3_f32 v4, v4, v63, v62
	v_max3_f32 v4, v4, v65, v64
	v_max3_f32 v4, v4, v59, v58
	v_max3_f32 v4, v4, v61, v60
	v_max3_f32 v4, v4, v55, v54
	v_max3_f32 v4, v4, v57, v56
	v_max3_f32 v4, v4, v51, v50
	v_max3_f32 v4, v4, v53, v52
	v_max3_f32 v4, v4, v77, v76
	v_max3_f32 v4, v4, v79, v78
	v_max3_f32 v4, v4, v81, v80
	v_max3_f32 v4, v4, v83, v82
	v_max3_f32 v4, v4, v85, v84
	v_max3_f32 v4, v4, v87, v86
	v_max3_f32 v4, v4, v89, v88
	v_max3_f32 v4, v4, v107, v90
	v_max3_f32 v4, v4, v31, v30
	v_max3_f32 v4, v4, v33, v32
	v_max3_f32 v4, v4, v27, v26
	v_max3_f32 v4, v4, v29, v28
	v_max3_f32 v4, v4, v23, v22
	v_max3_f32 v4, v4, v25, v24
	v_max3_f32 v4, v4, v19, v18
	v_max3_f32 v4, v4, v21, v20
	v_max3_f32 v4, v4, v15, v14
	v_max3_f32 v4, v4, v17, v16
	v_max3_f32 v4, v4, v11, v10
	v_max3_f32 v4, v4, v13, v12
	v_max3_f32 v4, v4, v7, v6
	v_max3_f32 v4, v4, v9, v8
	v_max3_f32 v4, v4, v108, v3
	v_mov_b32_e32 v5, v4
	s_nop 1
	v_permlane16_swap_b32_e32 v4, v5
	v_max_f32_e32 v5, v5, v5
	v_max_f32_e32 v4, v4, v4
	v_max_f32_e32 v4, v4, v5
	v_mov_b32_e32 v5, v4
	s_nop 1
	v_permlane32_swap_b32_e32 v4, v5
	v_max_f32_e32 v5, v5, v5
	v_max_f32_e32 v4, v4, v4
	v_max_f32_e32 v4, v4, v5
	v_sub_f32_e32 v5, v68, v4
	v_exp_f32_e32 v41, v5
	v_sub_f32_e32 v34, v67, v4
	v_exp_f32_e32 v43, v34
	v_sub_f32_e32 v34, v63, v4
	v_exp_f32_e32 v44, v34
	v_sub_f32_e32 v34, v62, v4
	v_exp_f32_e32 v45, v34
	v_sub_f32_e32 v34, v65, v4
	v_add_f32_e32 v5, 0, v41
	v_exp_f32_e32 v46, v34
	v_sub_f32_e32 v34, v64, v4
	v_add_f32_e32 v5, v43, v5
	v_exp_f32_e32 v47, v34
	v_sub_f32_e32 v34, v59, v4
	v_add_f32_e32 v5, v44, v5
	v_exp_f32_e32 v48, v34
	v_sub_f32_e32 v34, v58, v4
	v_add_f32_e32 v5, v45, v5
	v_exp_f32_e32 v49, v34
	v_sub_f32_e32 v34, v61, v4
	v_add_f32_e32 v5, v46, v5
	v_exp_f32_e32 v34, v34
	v_sub_f32_e32 v35, v60, v4
	v_add_f32_e32 v5, v47, v5
	v_exp_f32_e32 v35, v35
	v_sub_f32_e32 v36, v55, v4
	v_add_f32_e32 v5, v48, v5
	v_exp_f32_e32 v36, v36
	v_sub_f32_e32 v37, v54, v4
	v_add_f32_e32 v5, v49, v5
	v_exp_f32_e32 v37, v37
	v_sub_f32_e32 v38, v57, v4
	v_add_f32_e32 v5, v34, v5
	v_exp_f32_e32 v38, v38
	v_sub_f32_e32 v39, v56, v4
	v_add_f32_e32 v5, v35, v5
	v_exp_f32_e32 v39, v39
	v_sub_f32_e32 v40, v51, v4
	v_add_f32_e32 v5, v36, v5
	v_exp_f32_e32 v40, v40
	v_sub_f32_e32 v42, v50, v4
	v_add_f32_e32 v5, v37, v5
	v_exp_f32_e32 v42, v42
	v_sub_f32_e32 v50, v53, v4
	v_add_f32_e32 v5, v38, v5
	v_exp_f32_e32 v96, v50
	v_sub_f32_e32 v50, v52, v4
	v_add_f32_e32 v5, v39, v5
	v_exp_f32_e32 v98, v50
	v_sub_f32_e32 v50, v77, v4
	v_add_f32_e32 v5, v40, v5
	v_exp_f32_e32 v100, v50
	v_sub_f32_e32 v50, v76, v4
	v_add_f32_e32 v5, v42, v5
	v_exp_f32_e32 v102, v50
	v_sub_f32_e32 v50, v79, v4
	v_add_f32_e32 v5, v96, v5
	v_exp_f32_e32 v103, v50
	v_sub_f32_e32 v50, v78, v4
	v_add_f32_e32 v5, v98, v5
	v_exp_f32_e32 v104, v50
	v_sub_f32_e32 v50, v81, v4
	v_add_f32_e32 v5, v100, v5
	v_exp_f32_e32 v105, v50
	v_sub_f32_e32 v50, v80, v4
	v_add_f32_e32 v5, v102, v5
	v_exp_f32_e32 v106, v50
	v_sub_f32_e32 v50, v83, v4
	v_add_f32_e32 v5, v103, v5
	v_exp_f32_e32 v91, v50
	v_sub_f32_e32 v50, v82, v4
	v_add_f32_e32 v5, v104, v5
	v_exp_f32_e32 v92, v50
	v_sub_f32_e32 v50, v85, v4
	v_add_f32_e32 v5, v105, v5
	v_exp_f32_e32 v93, v50
	v_sub_f32_e32 v50, v84, v4
	v_add_f32_e32 v5, v106, v5
	v_exp_f32_e32 v94, v50
	v_sub_f32_e32 v50, v87, v4
	v_add_f32_e32 v5, v91, v5
	v_exp_f32_e32 v95, v50
	v_sub_f32_e32 v50, v86, v4
	v_add_f32_e32 v5, v92, v5
	v_exp_f32_e32 v97, v50
	v_sub_f32_e32 v50, v89, v4
	v_add_f32_e32 v5, v93, v5
	v_exp_f32_e32 v99, v50
	v_sub_f32_e32 v50, v88, v4
	v_add_f32_e32 v5, v94, v5
	v_exp_f32_e32 v101, v50
	v_sub_f32_e32 v50, v107, v4
	v_add_f32_e32 v5, v95, v5
	v_exp_f32_e32 v83, v50
	v_sub_f32_e32 v50, v90, v4
	v_add_f32_e32 v5, v97, v5
	v_exp_f32_e32 v84, v50
	v_sub_f32_e32 v31, v31, v4
	v_add_f32_e32 v5, v99, v5
	v_exp_f32_e32 v85, v31
	v_sub_f32_e32 v30, v30, v4
	v_add_f32_e32 v5, v101, v5
	v_exp_f32_e32 v86, v30
	v_sub_f32_e32 v30, v33, v4
	v_add_f32_e32 v5, v83, v5
	v_exp_f32_e32 v87, v30
	v_sub_f32_e32 v30, v32, v4
	v_add_f32_e32 v5, v84, v5
	v_exp_f32_e32 v88, v30
	v_sub_f32_e32 v27, v27, v4
	v_add_f32_e32 v5, v85, v5
	v_exp_f32_e32 v89, v27
	v_sub_f32_e32 v26, v26, v4
	v_add_f32_e32 v5, v86, v5
	v_exp_f32_e32 v90, v26
	v_sub_f32_e32 v26, v29, v4
	v_add_f32_e32 v5, v87, v5
	v_exp_f32_e32 v69, v26
	v_sub_f32_e32 v26, v28, v4
	v_add_f32_e32 v5, v88, v5
	v_exp_f32_e32 v76, v26
	v_sub_f32_e32 v23, v23, v4
	v_add_f32_e32 v5, v89, v5
	v_exp_f32_e32 v77, v23
	v_sub_f32_e32 v22, v22, v4
	v_add_f32_e32 v5, v90, v5
	v_exp_f32_e32 v78, v22
	v_sub_f32_e32 v22, v25, v4
	v_add_f32_e32 v5, v69, v5
	v_exp_f32_e32 v79, v22
	v_sub_f32_e32 v22, v24, v4
	v_add_f32_e32 v5, v76, v5
	v_exp_f32_e32 v80, v22
	v_sub_f32_e32 v19, v19, v4
	v_add_f32_e32 v5, v77, v5
	v_exp_f32_e32 v81, v19
	v_sub_f32_e32 v18, v18, v4
	v_add_f32_e32 v5, v78, v5
	v_exp_f32_e32 v82, v18
	v_sub_f32_e32 v18, v21, v4
	v_add_f32_e32 v5, v79, v5
	v_exp_f32_e32 v60, v18
	v_sub_f32_e32 v18, v20, v4
	v_add_f32_e32 v5, v80, v5
	v_exp_f32_e32 v61, v18
	v_sub_f32_e32 v15, v15, v4
	v_add_f32_e32 v5, v81, v5
	v_exp_f32_e32 v62, v15
	v_sub_f32_e32 v14, v14, v4
	v_add_f32_e32 v5, v82, v5
	v_exp_f32_e32 v63, v14
	v_sub_f32_e32 v14, v17, v4
	v_add_f32_e32 v5, v60, v5
	v_exp_f32_e32 v64, v14
	v_sub_f32_e32 v14, v16, v4
	v_add_f32_e32 v5, v61, v5
	v_exp_f32_e32 v65, v14
	v_sub_f32_e32 v11, v11, v4
	v_add_f32_e32 v5, v62, v5
	v_exp_f32_e32 v67, v11
	v_sub_f32_e32 v10, v10, v4
	v_add_f32_e32 v5, v63, v5
	v_exp_f32_e32 v68, v10
	v_sub_f32_e32 v10, v13, v4
	v_add_f32_e32 v5, v64, v5
	v_exp_f32_e32 v52, v10
	v_sub_f32_e32 v10, v12, v4
	v_add_f32_e32 v5, v65, v5
	v_exp_f32_e32 v53, v10
	v_sub_f32_e32 v7, v7, v4
	v_add_f32_e32 v5, v67, v5
	v_exp_f32_e32 v54, v7
	v_sub_f32_e32 v6, v6, v4
	v_add_f32_e32 v5, v68, v5
	v_exp_f32_e32 v55, v6
	v_sub_f32_e32 v6, v9, v4
	v_add_f32_e32 v5, v52, v5
	v_exp_f32_e32 v56, v6
	v_sub_f32_e32 v6, v8, v4
	v_add_f32_e32 v5, v53, v5
	v_exp_f32_e32 v57, v6
	v_sub_f32_e32 v6, v108, v4
	v_add_f32_e32 v5, v54, v5
	v_exp_f32_e32 v58, v6
	v_sub_f32_e32 v3, v3, v4
	v_add_f32_e32 v5, v55, v5
	v_exp_f32_e32 v59, v3
	v_add_f32_e32 v5, v56, v5
	v_add_f32_e32 v5, v57, v5
	v_add_f32_e32 v5, v58, v5
	v_add_f32_e32 v3, v59, v5
	v_and_b32_e32 v5, 64, v198
	v_xor_b32_e32 v4, 16, v198
	v_add_u32_e32 v5, 64, v5
	v_cmp_lt_i32_e32 vcc, v4, v5
	v_and_b32_e32 v2, 63, v75
	s_movk_i32 s0, 0x2800
	v_cndmask_b32_e32 v4, v198, v4, vcc
	v_lshlrev_b32_e32 v4, 2, v4
	ds_bpermute_b32 v4, v4, v3
	v_mul_lo_u32 v108, v0, s0
	v_lshrrev_b32_e32 v107, 3, v2
	s_or_b32 s0, s81, s30
	v_or_b32_e32 v0, s0, v107
	s_waitcnt lgkmcnt(0)
	v_add_f32_e32 v50, v3, v4
	v_xor_b32_e32 v3, 32, v198
	v_cmp_lt_i32_e32 vcc, v3, v5
	v_mul_u32_u24_e32 v0, 0x3e00, v0
	v_or_b32_e32 v110, 8, v107
	v_cndmask_b32_e32 v3, v198, v3, vcc
	v_lshlrev_b32_e32 v3, 2, v3
	ds_bpermute_b32 v51, v3, v50
	v_lshl_add_u64 v[2:3], s[36:37], 0, v[0:1]
	v_lshlrev_b32_e32 v0, 4, v75
	v_add_u32_e32 v6, s0, v110
	v_lshl_add_u64 v[2:3], v[2:3], 0, v[72:73]
	v_and_b32_e32 v0, 0x70, v0
	v_mul_u32_u24_e32 v6, 0x3e00, v6
	v_mov_b32_e32 v7, v1
	v_or_b32_e32 v111, 16, v107
	v_lshl_add_u64 v[2:3], v[2:3], 0, v[0:1]
	v_lshl_add_u64 v[6:7], s[36:37], 0, v[6:7]
	v_add_u32_e32 v10, s0, v111
	v_add_co_u32_e32 v2, vcc, s71, v2
	v_lshl_add_u64 v[6:7], v[6:7], 0, v[72:73]
	v_mul_u32_u24_e32 v10, 0x3e00, v10
	v_mov_b32_e32 v11, v1
	v_or_b32_e32 v112, 24, v107
	v_addc_co_u32_e32 v3, vcc, 0, v3, vcc
	v_lshl_add_u64 v[6:7], v[6:7], 0, v[0:1]
	v_lshl_add_u64 v[10:11], s[36:37], 0, v[10:11]
	v_add_u32_e32 v14, s0, v112
	v_add_co_u32_e32 v6, vcc, s71, v6
	v_lshl_add_u64 v[10:11], v[10:11], 0, v[72:73]
	v_mul_u32_u24_e32 v14, 0x3e00, v14
	v_mov_b32_e32 v15, v1
	s_or_b32 s0, s82, s30
	v_addc_co_u32_e32 v7, vcc, 0, v7, vcc
	v_lshl_add_u64 v[10:11], v[10:11], 0, v[0:1]
	v_lshl_add_u64 v[14:15], s[36:37], 0, v[14:15]
	v_or_b32_e32 v18, s0, v107
	v_add_co_u32_e32 v10, vcc, s71, v10
	v_lshl_add_u64 v[14:15], v[14:15], 0, v[72:73]
	v_mul_u32_u24_e32 v18, 0x3e00, v18
	v_mov_b32_e32 v19, v1
	v_addc_co_u32_e32 v11, vcc, 0, v11, vcc
	v_lshl_add_u64 v[14:15], v[14:15], 0, v[0:1]
	v_lshl_add_u64 v[18:19], s[36:37], 0, v[18:19]
	v_add_u32_e32 v22, s0, v110
	v_add_co_u32_e32 v14, vcc, s71, v14
	v_lshl_add_u64 v[18:19], v[18:19], 0, v[72:73]
	v_mul_u32_u24_e32 v22, 0x3e00, v22
	v_mov_b32_e32 v23, v1
	v_addc_co_u32_e32 v15, vcc, 0, v15, vcc
	v_lshl_add_u64 v[18:19], v[18:19], 0, v[0:1]
	v_lshl_add_u64 v[22:23], s[36:37], 0, v[22:23]
	v_add_u32_e32 v26, s0, v111
	v_add_co_u32_e32 v18, vcc, s71, v18
	v_lshl_add_u64 v[22:23], v[22:23], 0, v[72:73]
	v_mul_u32_u24_e32 v26, 0x3e00, v26
	v_mov_b32_e32 v27, v1
	global_load_dwordx4 v[2:5], v[2:3], off offset:3584
	v_addc_co_u32_e32 v19, vcc, 0, v19, vcc
	v_lshl_add_u64 v[22:23], v[22:23], 0, v[0:1]
	v_lshl_add_u64 v[26:27], s[36:37], 0, v[26:27]
	v_add_u32_e32 v30, s0, v112
	global_load_dwordx4 v[6:9], v[6:7], off offset:3584
	v_add_co_u32_e32 v22, vcc, s71, v22
	v_lshl_add_u64 v[26:27], v[26:27], 0, v[72:73]
	v_mul_u32_u24_e32 v30, 0x3e00, v30
	v_mov_b32_e32 v31, v1
	global_load_dwordx4 v[10:13], v[10:11], off offset:3584
	v_addc_co_u32_e32 v23, vcc, 0, v23, vcc
	v_lshl_add_u64 v[26:27], v[26:27], 0, v[0:1]
	v_lshl_add_u64 v[30:31], s[36:37], 0, v[30:31]
	global_load_dwordx4 v[14:17], v[14:15], off offset:3584
	v_add_co_u32_e32 v26, vcc, s71, v26
	v_lshl_add_u64 v[30:31], v[30:31], 0, v[72:73]
	global_load_dwordx4 v[18:21], v[18:19], off offset:3584
	v_addc_co_u32_e32 v27, vcc, 0, v27, vcc
	v_lshl_add_u64 v[30:31], v[30:31], 0, v[0:1]
	global_load_dwordx4 v[22:25], v[22:23], off offset:3584
	v_add_co_u32_e32 v30, vcc, s71, v30
	global_load_dwordx4 v[26:29], v[26:27], off offset:3584
	s_nop 0
	v_addc_co_u32_e32 v31, vcc, 0, v31, vcc
	global_load_dwordx4 v[30:33], v[30:31], off offset:3584
	v_lshrrev_b32_e32 v74, 2, v74
	v_lshlrev_b32_e32 v109, 3, v75
	v_or_b32_e32 v74, v66, v74
	v_add_u32_e32 v75, 0, v108
	v_and_b32_e32 v108, 24, v109
	v_mul_u32_u24_e32 v74, 0xa0, v74
	v_add3_u32 v74, v75, v108, v74
	v_mul_u32_u24_e32 v108, 0xa0, v107
	v_add3_u32 v75, v75, v0, v108
	v_add_u32_e32 v108, s30, v112
	s_waitcnt lgkmcnt(0)
	s_waitcnt vmcnt(7)
	ds_write_b128 v75, v[2:5]
	s_waitcnt vmcnt(6)
	ds_write_b128 v75, v[6:9] offset:1280
	s_waitcnt vmcnt(5)
	ds_write_b128 v75, v[10:13] offset:2560
	s_waitcnt vmcnt(4)
	ds_write_b128 v75, v[14:17] offset:3840
	s_waitcnt vmcnt(3)
	ds_write_b128 v75, v[18:21] offset:5120
	s_waitcnt vmcnt(2)
	ds_write_b128 v75, v[22:25] offset:6400
	s_waitcnt vmcnt(1)
	ds_write_b128 v75, v[26:29] offset:7680
	s_waitcnt vmcnt(0)
	ds_write_b128 v75, v[30:33] offset:8960
	v_add_u32_e32 v2, s80, v108
	v_mul_u32_u24_e32 v2, 0x3e00, v2
	v_mov_b32_e32 v3, v1
	v_add_u32_e32 v109, s30, v111
	v_lshl_add_u64 v[2:3], s[36:37], 0, v[2:3]
	v_add_u32_e32 v6, s80, v109
	v_lshl_add_u64 v[2:3], v[2:3], 0, v[72:73]
	v_mul_u32_u24_e32 v6, 0x3e00, v6
	v_mov_b32_e32 v7, v1
	v_add_u32_e32 v110, s30, v110
	v_lshl_add_u64 v[2:3], v[2:3], 0, v[0:1]
	v_lshl_add_u64 v[6:7], s[36:37], 0, v[6:7]
	v_add_u32_e32 v10, s80, v110
	v_add_co_u32_e32 v2, vcc, s71, v2
	v_lshl_add_u64 v[6:7], v[6:7], 0, v[72:73]
	v_mul_u32_u24_e32 v10, 0x3e00, v10
	v_mov_b32_e32 v11, v1
	s_or_b32 s0, s30, s80
	v_addc_co_u32_e32 v3, vcc, 0, v3, vcc
	v_lshl_add_u64 v[6:7], v[6:7], 0, v[0:1]
	v_lshl_add_u64 v[10:11], s[36:37], 0, v[10:11]
	v_or_b32_e32 v14, s0, v107
	v_add_co_u32_e32 v6, vcc, s71, v6
	v_lshl_add_u64 v[10:11], v[10:11], 0, v[72:73]
	v_mul_u32_u24_e32 v14, 0x3e00, v14
	v_mov_b32_e32 v15, v1
	v_addc_co_u32_e32 v7, vcc, 0, v7, vcc
	v_lshl_add_u64 v[10:11], v[10:11], 0, v[0:1]
	v_lshl_add_u64 v[14:15], s[36:37], 0, v[14:15]
	v_add_u32_e32 v18, s79, v108
	v_add_co_u32_e32 v10, vcc, s71, v10
	v_lshl_add_u64 v[14:15], v[14:15], 0, v[72:73]
	v_mul_u32_u24_e32 v18, 0x3e00, v18
	v_mov_b32_e32 v19, v1
	v_addc_co_u32_e32 v11, vcc, 0, v11, vcc
	v_lshl_add_u64 v[14:15], v[14:15], 0, v[0:1]
	v_lshl_add_u64 v[18:19], s[36:37], 0, v[18:19]
	v_add_u32_e32 v22, s79, v109
	v_add_co_u32_e32 v14, vcc, s71, v14
	v_lshl_add_u64 v[18:19], v[18:19], 0, v[72:73]
	v_mul_u32_u24_e32 v22, 0x3e00, v22
	v_mov_b32_e32 v23, v1
	v_addc_co_u32_e32 v15, vcc, 0, v15, vcc
	v_lshl_add_u64 v[18:19], v[18:19], 0, v[0:1]
	v_lshl_add_u64 v[22:23], s[36:37], 0, v[22:23]
	v_add_u32_e32 v26, s79, v110
	v_add_co_u32_e32 v18, vcc, s71, v18
	v_lshl_add_u64 v[22:23], v[22:23], 0, v[72:73]
	v_mul_u32_u24_e32 v26, 0x3e00, v26
	v_mov_b32_e32 v27, v1
	s_or_b32 s0, s30, s79
	v_addc_co_u32_e32 v19, vcc, 0, v19, vcc
	v_lshl_add_u64 v[22:23], v[22:23], 0, v[0:1]
	v_lshl_add_u64 v[26:27], s[36:37], 0, v[26:27]
	v_or_b32_e32 v30, s0, v107
	v_add_co_u32_e32 v22, vcc, s71, v22
	v_lshl_add_u64 v[26:27], v[26:27], 0, v[72:73]
	v_mul_u32_u24_e32 v30, 0x3e00, v30
	v_mov_b32_e32 v31, v1
	v_addc_co_u32_e32 v23, vcc, 0, v23, vcc
	v_lshl_add_u64 v[26:27], v[26:27], 0, v[0:1]
	v_lshl_add_u64 v[30:31], s[36:37], 0, v[30:31]
	v_add_co_u32_e32 v26, vcc, s71, v26
	v_lshl_add_u64 v[30:31], v[30:31], 0, v[72:73]
	s_nop 0
	v_addc_co_u32_e32 v27, vcc, 0, v27, vcc
	v_lshl_add_u64 v[30:31], v[30:31], 0, v[0:1]
	v_add_co_u32_e32 v30, vcc, s71, v30
	global_load_dwordx4 v[26:29], v[26:27], off offset:3584
	s_nop 0
	v_addc_co_u32_e32 v31, vcc, 0, v31, vcc
	global_load_dwordx4 v[30:33], v[30:31], off offset:3584
	v_cvt_pk_bf16_f32 v113, v44, v45
	global_load_dwordx4 v[18:21], v[18:19], off offset:3584
	v_cvt_pk_bf16_f32 v114, v46, v47
	global_load_dwordx4 v[22:25], v[22:23], off offset:3584
	v_cvt_pk_bf16_f32 v112, v41, v43
	global_load_dwordx4 v[10:13], v[10:11], off offset:3584
	v_cvt_pk_bf16_f32 v115, v48, v49
	global_load_dwordx4 v[14:17], v[14:15], off offset:3584
	s_or_b32 s0, s30, s78
	global_load_dwordx4 v[2:5], v[2:3], off offset:3584
	v_cvt_pk_bf16_f32 v85, v85, v86
	global_load_dwordx4 v[6:9], v[6:7], off offset:3584
	s_waitcnt lgkmcnt(0)
	ds_read_b64_tr_b16 v[46:47], v74 offset:2560
	ds_read_b64_tr_b16 v[44:45], v74
	ds_read_b64_tr_b16 v[116:117], v74 offset:32
	ds_read_b64_tr_b16 v[118:119], v74 offset:2592
	ds_read_b64_tr_b16 v[120:121], v74 offset:64
	ds_read_b64_tr_b16 v[122:123], v74 offset:2624
	ds_read_b64_tr_b16 v[124:125], v74 offset:96
	ds_read_b64_tr_b16 v[126:127], v74 offset:2656
	s_waitcnt lgkmcnt(6)
	v_mfma_f32_16x16x32_bf16 v[44:47], v[44:47], v[112:115], 0
	v_cvt_pk_bf16_f32 v86, v87, v88
	v_cvt_pk_bf16_f32 v87, v89, v90
	v_cvt_pk_bf16_f32 v84, v83, v84
	s_waitcnt lgkmcnt(4)
	v_mfma_f32_16x16x32_bf16 v[116:119], v[116:119], v[112:115], 0
	v_cvt_pk_bf16_f32 v77, v77, v78
	v_cvt_pk_bf16_f32 v78, v79, v80
	v_cvt_pk_bf16_f32 v79, v81, v82
	s_waitcnt lgkmcnt(2)
	v_mfma_f32_16x16x32_bf16 v[120:123], v[120:123], v[112:115], 0
	v_cvt_pk_bf16_f32 v76, v69, v76
	s_waitcnt lgkmcnt(0)
	v_mfma_f32_16x16x32_bf16 v[112:115], v[124:127], v[112:115], 0
	v_cvt_pk_bf16_f32 v124, v34, v35
	v_cvt_pk_bf16_f32 v125, v36, v37
	ds_read_b64_tr_b16 v[34:35], v74 offset:5120
	ds_read_b64_tr_b16 v[36:37], v74 offset:7680
	v_cvt_pk_bf16_f32 v126, v38, v39
	v_cvt_pk_bf16_f32 v127, v40, v42
	s_waitcnt lgkmcnt(0)
	s_nop 0
	v_mfma_f32_16x16x32_bf16 v[42:45], v[34:37], v[124:127], v[44:47]
	ds_read_b64_tr_b16 v[34:35], v74 offset:5152
	ds_read_b64_tr_b16 v[36:37], v74 offset:7712
	s_waitcnt lgkmcnt(0)
	v_mfma_f32_16x16x32_bf16 v[38:41], v[34:37], v[124:127], v[116:119]
	ds_read_b64_tr_b16 v[34:35], v74 offset:5184
	ds_read_b64_tr_b16 v[36:37], v74 offset:7744
	ds_read_b64_tr_b16 v[46:47], v74 offset:5216
	ds_read_b64_tr_b16 v[48:49], v74 offset:7776
	s_waitcnt lgkmcnt(0)
	s_waitcnt vmcnt(6)
	ds_write_b128 v75, v[30:33]
	ds_write_b128 v75, v[26:29] offset:1280
	s_waitcnt vmcnt(4)
	ds_write_b128 v75, v[22:25] offset:2560
	ds_write_b128 v75, v[18:21] offset:3840
	s_waitcnt vmcnt(2)
	ds_write_b128 v75, v[14:17] offset:5120
	ds_write_b128 v75, v[10:13] offset:6400
	s_waitcnt vmcnt(0)
	ds_write_b128 v75, v[6:9] offset:7680
	ds_write_b128 v75, v[2:5] offset:8960
	v_add_u32_e32 v2, s78, v108
	v_mul_u32_u24_e32 v2, 0x3e00, v2
	v_mov_b32_e32 v3, v1
	v_lshl_add_u64 v[2:3], s[36:37], 0, v[2:3]
	v_add_u32_e32 v6, s78, v109
	v_lshl_add_u64 v[2:3], v[2:3], 0, v[72:73]
	v_mul_u32_u24_e32 v6, 0x3e00, v6
	v_mov_b32_e32 v7, v1
	v_lshl_add_u64 v[2:3], v[2:3], 0, v[0:1]
	v_lshl_add_u64 v[6:7], s[36:37], 0, v[6:7]
	v_add_u32_e32 v10, s78, v110
	v_add_co_u32_e32 v2, vcc, s71, v2
	v_lshl_add_u64 v[6:7], v[6:7], 0, v[72:73]
	v_mul_u32_u24_e32 v10, 0x3e00, v10
	v_mov_b32_e32 v11, v1
	v_addc_co_u32_e32 v3, vcc, 0, v3, vcc
	v_lshl_add_u64 v[6:7], v[6:7], 0, v[0:1]
	v_lshl_add_u64 v[10:11], s[36:37], 0, v[10:11]
	v_or_b32_e32 v14, s0, v107
	v_add_co_u32_e32 v6, vcc, s71, v6
	v_lshl_add_u64 v[10:11], v[10:11], 0, v[72:73]
	v_mul_u32_u24_e32 v14, 0x3e00, v14
	v_mov_b32_e32 v15, v1
	v_addc_co_u32_e32 v7, vcc, 0, v7, vcc
	v_lshl_add_u64 v[10:11], v[10:11], 0, v[0:1]
	v_lshl_add_u64 v[14:15], s[36:37], 0, v[14:15]
	v_add_u32_e32 v18, s70, v108
	v_add_co_u32_e32 v10, vcc, s71, v10
	v_lshl_add_u64 v[14:15], v[14:15], 0, v[72:73]
	v_mul_u32_u24_e32 v18, 0x3e00, v18
	v_mov_b32_e32 v19, v1
	v_addc_co_u32_e32 v11, vcc, 0, v11, vcc
	v_lshl_add_u64 v[14:15], v[14:15], 0, v[0:1]
	v_lshl_add_u64 v[18:19], s[36:37], 0, v[18:19]
	v_add_u32_e32 v22, s70, v109
	v_add_co_u32_e32 v14, vcc, s71, v14
	v_lshl_add_u64 v[18:19], v[18:19], 0, v[72:73]
	v_mul_u32_u24_e32 v22, 0x3e00, v22
	v_mov_b32_e32 v23, v1
	v_addc_co_u32_e32 v15, vcc, 0, v15, vcc
	v_lshl_add_u64 v[18:19], v[18:19], 0, v[0:1]
	v_lshl_add_u64 v[22:23], s[36:37], 0, v[22:23]
	v_add_co_u32_e32 v18, vcc, s71, v18
	v_lshl_add_u64 v[22:23], v[22:23], 0, v[72:73]
	s_nop 0
	v_addc_co_u32_e32 v19, vcc, 0, v19, vcc
	v_lshl_add_u64 v[22:23], v[22:23], 0, v[0:1]
	v_add_co_u32_e32 v22, vcc, s71, v22
	global_load_dwordx4 v[18:21], v[18:19], off offset:3584
	s_nop 0
	v_addc_co_u32_e32 v23, vcc, 0, v23, vcc
	global_load_dwordx4 v[26:29], v[22:23], off offset:3584
	v_add_u32_e32 v22, s70, v110
	v_mul_u32_u24_e32 v22, 0x3e00, v22
	v_mov_b32_e32 v23, v1
	v_lshl_add_u64 v[22:23], s[36:37], 0, v[22:23]
	v_lshl_add_u64 v[22:23], v[22:23], 0, v[72:73]
	v_lshl_add_u64 v[22:23], v[22:23], 0, v[0:1]
	v_add_co_u32_e32 v22, vcc, s71, v22
	s_or_b32 s0, s30, s70
	s_nop 0
	v_addc_co_u32_e32 v23, vcc, 0, v23, vcc
	global_load_dwordx4 v[30:33], v[22:23], off offset:3584
	v_or_b32_e32 v22, s0, v107
	v_mul_u32_u24_e32 v22, 0x3e00, v22
	v_mov_b32_e32 v23, v1
	v_lshl_add_u64 v[22:23], s[36:37], 0, v[22:23]
	v_lshl_add_u64 v[22:23], v[22:23], 0, v[72:73]
	v_lshl_add_u64 v[22:23], v[22:23], 0, v[0:1]
	v_add_co_u32_e32 v22, vcc, s71, v22
	v_mfma_f32_16x16x32_bf16 v[46:49], v[46:49], v[124:127], v[112:115]
	s_nop 0
	v_addc_co_u32_e32 v23, vcc, 0, v23, vcc
	global_load_dwordx4 v[10:13], v[10:11], off offset:3584
	v_cvt_pk_bf16_f32 v24, v103, v104
	global_load_dwordx4 v[112:115], v[22:23], off offset:3584
	v_cvt_pk_bf16_f32 v23, v100, v102
	global_load_dwordx4 v[14:17], v[14:15], off offset:3584
	v_cvt_pk_bf16_f32 v25, v105, v106
	global_load_dwordx4 v[2:5], v[2:3], off offset:3584
	v_cvt_pk_bf16_f32 v22, v96, v98
	global_load_dwordx4 v[6:9], v[6:7], off offset:3584
	s_waitcnt lgkmcnt(0)
	ds_read_b64_tr_b16 v[104:105], v74 offset:2560
	ds_read_b64_tr_b16 v[102:103], v74
	ds_read_b64_tr_b16 v[116:117], v74 offset:32
	s_waitcnt lgkmcnt(1)
	v_mfma_f32_16x16x32_bf16 v[42:45], v[102:105], v[22:25], v[42:45]
	ds_read_b64_tr_b16 v[118:119], v74 offset:2592
	ds_read_b64_tr_b16 v[102:103], v74 offset:64
	ds_read_b64_tr_b16 v[104:105], v74 offset:2624
	s_or_b32 s0, s30, s68
	v_mfma_f32_16x16x32_bf16 v[34:37], v[34:37], v[124:127], v[120:123]
	s_waitcnt lgkmcnt(0)
	v_mfma_f32_16x16x32_bf16 v[102:105], v[102:105], v[22:25], v[34:37]
	s_nop 5
	ds_read_b64_tr_b16 v[34:35], v74 offset:96
	ds_read_b64_tr_b16 v[36:37], v74 offset:2656
	v_mfma_f32_16x16x32_bf16 v[38:41], v[116:119], v[22:25], v[38:41]
	s_waitcnt lgkmcnt(0)
	v_mfma_f32_16x16x32_bf16 v[22:25], v[34:37], v[22:25], v[46:49]
	ds_read_b64_tr_b16 v[34:35], v74 offset:5120
	ds_read_b64_tr_b16 v[36:37], v74 offset:7680
	s_nop 0
	v_cvt_pk_bf16_f32 v46, v91, v92
	v_cvt_pk_bf16_f32 v47, v93, v94
	v_cvt_pk_bf16_f32 v48, v95, v97
	v_cvt_pk_bf16_f32 v49, v99, v101
	s_waitcnt lgkmcnt(0)
	s_nop 0
	v_mfma_f32_16x16x32_bf16 v[34:37], v[34:37], v[46:49], v[42:45]
	s_nop 2
	ds_read_b64_tr_b16 v[42:43], v74 offset:5152
	ds_read_b64_tr_b16 v[44:45], v74 offset:7712
	s_waitcnt lgkmcnt(0)
	v_mfma_f32_16x16x32_bf16 v[42:45], v[42:45], v[46:49], v[38:41]
	s_nop 2
	ds_read_b64_tr_b16 v[38:39], v74 offset:5184
	ds_read_b64_tr_b16 v[40:41], v74 offset:7744
	ds_read_b64_tr_b16 v[92:93], v74 offset:5216
	ds_read_b64_tr_b16 v[94:95], v74 offset:7776
	s_waitcnt lgkmcnt(0)
	s_waitcnt vmcnt(3)
	ds_write_b128 v75, v[112:115]
	ds_write_b128 v75, v[30:33] offset:1280
	ds_write_b128 v75, v[26:29] offset:2560
	ds_write_b128 v75, v[18:21] offset:3840
	s_waitcnt vmcnt(2)
	ds_write_b128 v75, v[14:17] offset:5120
	ds_write_b128 v75, v[10:13] offset:6400
	s_waitcnt vmcnt(0)
	ds_write_b128 v75, v[6:9] offset:7680
	ds_write_b128 v75, v[2:5] offset:8960
	v_add_u32_e32 v2, s68, v108
	v_mul_u32_u24_e32 v2, 0x3e00, v2
	v_mov_b32_e32 v3, v1
	v_lshl_add_u64 v[2:3], s[36:37], 0, v[2:3]
	v_add_u32_e32 v6, s68, v109
	v_lshl_add_u64 v[2:3], v[2:3], 0, v[72:73]
	v_mul_u32_u24_e32 v6, 0x3e00, v6
	v_mov_b32_e32 v7, v1
	v_lshl_add_u64 v[2:3], v[2:3], 0, v[0:1]
	v_lshl_add_u64 v[6:7], s[36:37], 0, v[6:7]
	v_add_u32_e32 v10, s68, v110
	v_add_co_u32_e32 v2, vcc, s71, v2
	v_lshl_add_u64 v[6:7], v[6:7], 0, v[72:73]
	v_mul_u32_u24_e32 v10, 0x3e00, v10
	v_mov_b32_e32 v11, v1
	v_addc_co_u32_e32 v3, vcc, 0, v3, vcc
	v_lshl_add_u64 v[6:7], v[6:7], 0, v[0:1]
	v_lshl_add_u64 v[10:11], s[36:37], 0, v[10:11]
	v_or_b32_e32 v14, s0, v107
	v_add_co_u32_e32 v6, vcc, s71, v6
	v_lshl_add_u64 v[10:11], v[10:11], 0, v[72:73]
	v_mul_u32_u24_e32 v14, 0x3e00, v14
	v_mov_b32_e32 v15, v1
	v_addc_co_u32_e32 v7, vcc, 0, v7, vcc
	v_lshl_add_u64 v[10:11], v[10:11], 0, v[0:1]
	v_lshl_add_u64 v[14:15], s[36:37], 0, v[14:15]
	v_add_u32_e32 v18, s31, v108
	v_add_co_u32_e32 v10, vcc, s71, v10
	v_lshl_add_u64 v[14:15], v[14:15], 0, v[72:73]
	v_mul_u32_u24_e32 v18, 0x3e00, v18
	v_mov_b32_e32 v19, v1
	v_addc_co_u32_e32 v11, vcc, 0, v11, vcc
	v_lshl_add_u64 v[14:15], v[14:15], 0, v[0:1]
	v_lshl_add_u64 v[18:19], s[36:37], 0, v[18:19]
	v_add_u32_e32 v26, s31, v109
	v_add_co_u32_e32 v14, vcc, s71, v14
	v_lshl_add_u64 v[18:19], v[18:19], 0, v[72:73]
	v_mul_u32_u24_e32 v26, 0x3e00, v26
	v_mov_b32_e32 v27, v1
	v_addc_co_u32_e32 v15, vcc, 0, v15, vcc
	v_lshl_add_u64 v[18:19], v[18:19], 0, v[0:1]
	v_lshl_add_u64 v[26:27], s[36:37], 0, v[26:27]
	v_add_u32_e32 v30, s31, v110
	v_add_co_u32_e32 v18, vcc, s71, v18
	v_lshl_add_u64 v[26:27], v[26:27], 0, v[72:73]
	v_mul_u32_u24_e32 v30, 0x3e00, v30
	v_mov_b32_e32 v31, v1
	s_or_b32 s0, s30, s31
	v_mfma_f32_16x16x32_bf16 v[38:41], v[38:41], v[46:49], v[102:105]
	v_addc_co_u32_e32 v19, vcc, 0, v19, vcc
	v_lshl_add_u64 v[26:27], v[26:27], 0, v[0:1]
	v_mfma_f32_16x16x32_bf16 v[22:25], v[92:95], v[46:49], v[22:25]
	v_lshl_add_u64 v[30:31], s[36:37], 0, v[30:31]
	v_or_b32_e32 v46, s0, v107
	v_add_co_u32_e32 v26, vcc, s71, v26
	v_lshl_add_u64 v[30:31], v[30:31], 0, v[72:73]
	v_mul_u32_u24_e32 v46, 0x3e00, v46
	v_mov_b32_e32 v47, v1
	v_addc_co_u32_e32 v27, vcc, 0, v27, vcc
	v_lshl_add_u64 v[30:31], v[30:31], 0, v[0:1]
	v_lshl_add_u64 v[46:47], s[36:37], 0, v[46:47]
	v_add_co_u32_e32 v30, vcc, s71, v30
	v_lshl_add_u64 v[46:47], v[46:47], 0, v[72:73]
	s_nop 0
	v_addc_co_u32_e32 v31, vcc, 0, v31, vcc
	v_lshl_add_u64 v[46:47], v[46:47], 0, v[0:1]
	v_add_co_u32_e32 v46, vcc, s71, v46
	global_load_dwordx4 v[30:33], v[30:31], off offset:3584
	s_nop 0
	v_addc_co_u32_e32 v47, vcc, 0, v47, vcc
	global_load_dwordx4 v[46:49], v[46:47], off offset:3584
	s_andn2_b64 vcc, exec, s[6:7]
	global_load_dwordx4 v[18:21], v[18:19], off offset:3584
	s_nop 0
	global_load_dwordx4 v[26:29], v[26:27], off offset:3584
	s_nop 0
	global_load_dwordx4 v[10:13], v[10:11], off offset:3584
	s_nop 0
	global_load_dwordx4 v[14:17], v[14:15], off offset:3584
	s_nop 0
	global_load_dwordx4 v[2:5], v[2:3], off offset:3584
	s_nop 0
	global_load_dwordx4 v[6:9], v[6:7], off offset:3584
	s_waitcnt lgkmcnt(0)
	ds_read_b64_tr_b16 v[90:91], v74 offset:2560
	ds_read_b64_tr_b16 v[88:89], v74
	ds_read_b64_tr_b16 v[92:93], v74 offset:32
	s_waitcnt lgkmcnt(1)
	v_mfma_f32_16x16x32_bf16 v[34:37], v[88:91], v[84:87], v[34:37]
	ds_read_b64_tr_b16 v[94:95], v74 offset:2592
	ds_read_b64_tr_b16 v[88:89], v74 offset:64
	ds_read_b64_tr_b16 v[90:91], v74 offset:2624
	s_waitcnt lgkmcnt(0)
	v_mfma_f32_16x16x32_bf16 v[38:41], v[88:91], v[84:87], v[38:41]
	ds_read_b64_tr_b16 v[88:89], v74 offset:96
	ds_read_b64_tr_b16 v[90:91], v74 offset:2656
	ds_read_b64_tr_b16 v[80:81], v74 offset:5120
	ds_read_b64_tr_b16 v[82:83], v74 offset:7680
	s_waitcnt lgkmcnt(0)
	v_mfma_f32_16x16x32_bf16 v[34:37], v[80:83], v[76:79], v[34:37]
	ds_read_b64_tr_b16 v[80:81], v74 offset:5152
	ds_read_b64_tr_b16 v[82:83], v74 offset:7712
	v_mfma_f32_16x16x32_bf16 v[42:45], v[92:95], v[84:87], v[42:45]
	s_waitcnt lgkmcnt(0)
	v_mfma_f32_16x16x32_bf16 v[42:45], v[80:83], v[76:79], v[42:45]
	ds_read_b64_tr_b16 v[80:81], v74 offset:5184
	ds_read_b64_tr_b16 v[82:83], v74 offset:7744
	s_waitcnt lgkmcnt(0)
	v_mfma_f32_16x16x32_bf16 v[38:41], v[80:83], v[76:79], v[38:41]
	ds_read_b64_tr_b16 v[80:81], v74 offset:5216
	ds_read_b64_tr_b16 v[82:83], v74 offset:7776
	s_waitcnt lgkmcnt(0)
	s_waitcnt vmcnt(6)
	ds_write_b128 v75, v[46:49]
	ds_write_b128 v75, v[30:33] offset:1280
	s_waitcnt vmcnt(4)
	ds_write_b128 v75, v[26:29] offset:2560
	ds_write_b128 v75, v[18:21] offset:3840
	s_waitcnt vmcnt(2)
	ds_write_b128 v75, v[14:17] offset:5120
	ds_write_b128 v75, v[10:13] offset:6400
	s_waitcnt vmcnt(0)
	ds_write_b128 v75, v[6:9] offset:7680
	ds_write_b128 v75, v[2:5] offset:8960
	s_waitcnt lgkmcnt(0)
	ds_read_b64_tr_b16 v[8:9], v74 offset:2560
	ds_read_b64_tr_b16 v[6:7], v74
	ds_read_b64_tr_b16 v[10:11], v74 offset:32
	ds_read_b64_tr_b16 v[12:13], v74 offset:2592
	v_mfma_f32_16x16x32_bf16 v[22:25], v[88:91], v[84:87], v[22:25]
	ds_read_b64_tr_b16 v[14:15], v74 offset:64
	ds_read_b64_tr_b16 v[16:17], v74 offset:2624
	ds_read_b64_tr_b16 v[18:19], v74 offset:96
	ds_read_b64_tr_b16 v[20:21], v74 offset:2656
	v_cvt_pk_bf16_f32 v2, v60, v61
	v_mfma_f32_16x16x32_bf16 v[22:25], v[80:83], v[76:79], v[22:25]
	v_cvt_pk_bf16_f32 v3, v62, v63
	v_cvt_pk_bf16_f32 v4, v64, v65
	v_cvt_pk_bf16_f32 v5, v67, v68
	s_waitcnt lgkmcnt(6)
	s_nop 0
	v_mfma_f32_16x16x32_bf16 v[6:9], v[6:9], v[2:5], v[34:37]
	s_waitcnt lgkmcnt(4)
	v_mfma_f32_16x16x32_bf16 v[10:13], v[10:13], v[2:5], v[42:45]
	s_waitcnt lgkmcnt(2)
	v_mfma_f32_16x16x32_bf16 v[14:17], v[14:17], v[2:5], v[38:41]
	s_waitcnt lgkmcnt(0)
	v_mfma_f32_16x16x32_bf16 v[18:21], v[18:21], v[2:5], v[22:25]
	ds_read_b64_tr_b16 v[2:3], v74 offset:5120
	ds_read_b64_tr_b16 v[4:5], v74 offset:7680
	s_nop 0
	v_cvt_pk_bf16_f32 v22, v52, v53
	v_cvt_pk_bf16_f32 v23, v54, v55
	v_cvt_pk_bf16_f32 v24, v56, v57
	v_cvt_pk_bf16_f32 v25, v58, v59
	s_waitcnt lgkmcnt(0)
	s_nop 0
	v_mfma_f32_16x16x32_bf16 v[2:5], v[2:5], v[22:25], v[6:9]
	s_nop 2
	ds_read_b64_tr_b16 v[6:7], v74 offset:5152
	ds_read_b64_tr_b16 v[8:9], v74 offset:7712
	s_waitcnt lgkmcnt(0)
	v_mfma_f32_16x16x32_bf16 v[6:9], v[6:9], v[22:25], v[10:13]
	s_nop 2
	ds_read_b64_tr_b16 v[10:11], v74 offset:5184
	ds_read_b64_tr_b16 v[12:13], v74 offset:7744
	s_waitcnt lgkmcnt(0)
	v_mfma_f32_16x16x32_bf16 v[10:13], v[10:13], v[22:25], v[14:17]
	s_nop 2
	ds_read_b64_tr_b16 v[14:15], v74 offset:5216
	ds_read_b64_tr_b16 v[16:17], v74 offset:7776
	s_waitcnt lgkmcnt(0)
	v_mfma_f32_16x16x32_bf16 v[14:17], v[14:17], v[22:25], v[18:21]
	s_cbranch_vccnz .LBB0_397
	s_nop 1
	v_add_f32_e32 v20, v50, v51
	v_div_scale_f32 v21, s[0:1], v20, v20, 1.0
	v_rcp_f32_e32 v22, v21
	v_lshlrev_b32_e32 v0, 1, v66
	v_lshl_add_u64 v[18:19], v[70:71], 0, v[0:1]
	v_fma_f32 v0, -v21, v22, 1.0
	v_fmac_f32_e32 v22, v0, v22
	v_div_scale_f32 v0, vcc, 1.0, v20, 1.0
	v_mul_f32_e32 v23, v0, v22
	v_fma_f32 v24, -v21, v23, v0
	v_fmac_f32_e32 v23, v24, v22
	v_fma_f32 v0, -v21, v23, v0
	v_div_fmas_f32 v0, v0, v22, v23
	v_div_fixup_f32 v0, v0, v20, 1.0
	v_pk_mul_f32 v[2:3], v[0:1], v[2:3] op_sel_hi:[0,1]
	v_pk_mul_f32 v[4:5], v[0:1], v[4:5] op_sel_hi:[0,1]
	v_cvt_pk_bf16_f32 v2, v2, v3
	v_cvt_pk_bf16_f32 v3, v4, v5
	global_store_dwordx2 v[18:19], v[2:3], off
	v_pk_mul_f32 v[2:3], v[0:1], v[6:7] op_sel_hi:[0,1]
	v_pk_mul_f32 v[4:5], v[0:1], v[8:9] op_sel_hi:[0,1]
	v_cvt_pk_bf16_f32 v2, v2, v3
	v_cvt_pk_bf16_f32 v3, v4, v5
	global_store_dwordx2 v[18:19], v[2:3], off offset:32
	v_pk_mul_f32 v[2:3], v[0:1], v[10:11] op_sel_hi:[0,1]
	v_pk_mul_f32 v[4:5], v[0:1], v[12:13] op_sel_hi:[0,1]
	v_cvt_pk_bf16_f32 v2, v2, v3
	v_cvt_pk_bf16_f32 v3, v4, v5
	global_store_dwordx2 v[18:19], v[2:3], off offset:64
	v_pk_mul_f32 v[2:3], v[0:1], v[14:15] op_sel_hi:[0,1]
	v_pk_mul_f32 v[4:5], v[0:1], v[16:17] op_sel_hi:[0,1]
	v_cvt_pk_bf16_f32 v2, v2, v3
	v_cvt_pk_bf16_f32 v3, v4, v5
	global_store_dwordx2 v[18:19], v[2:3], off offset:96
	s_branch .LBB0_397

.LBB0_610:
	s_ashr_i32 s5, s23, 7
	s_bfe_u32 s4, s23, 0x20005
	s_mul_hi_i32 s8, s5, 0x3e00000
	s_mul_i32 s5, s5, 0x3e00000
	s_add_u32 s18, s2, s5
	s_addc_u32 s19, s17, s8
	s_lshl_b32 s5, s23, 7
	s_and_b32 s5, s5, 0xf80
	v_and_b32_e32 v64, 15, v2
	v_lshl_add_u32 v0, v3, 4, s5
	v_or_b32_e32 v66, v0, v64
	v_mov_b64_e32 v[20:21], s[18:19]
	v_mad_i64_i32 v[4:5], s[18:19], v66, s65, v[20:21]
	s_lshl_b32 s8, s4, 8
	v_bfe_u32 v65, v2, 4, 2
	v_lshl_add_u64 v[4:5], v[4:5], 0, s[8:9]
	s_mov_b64 s[18:19], 0x2200
	v_lshl_add_u64 v[132:133], v[4:5], 0, s[18:19]
	v_lshlrev_b32_e32 v0, 4, v65
	v_lshl_add_u64 v[16:17], v[132:133], 0, v[0:1]
	v_ashrrev_i32_e32 v67, 4, v2
	global_load_dwordx4 v[4:7], v[16:17], off
	global_load_dwordx4 v[8:11], v[16:17], off offset:64
	global_load_dwordx4 v[12:15], v[16:17], off offset:128
	s_nop 0
	global_load_dwordx4 v[16:19], v[16:17], off offset:192
	v_lshlrev_b32_e32 v0, 4, v2
	v_mad_i64_i32 v[20:21], s[18:19], v67, s65, v[20:21]
	v_lshl_add_u64 v[20:21], v[20:21], 0, s[8:9]
	v_and_b32_e32 v0, 0xf0, v0
	v_lshl_add_u64 v[36:37], v[20:21], 0, v[0:1]
	v_add_co_u32_e32 v24, vcc, s64, v36
	s_mov_b32 s5, 0x7e000
	s_nop 0
	v_addc_co_u32_e32 v25, vcc, 0, v37, vcc
	v_add_co_u32_e32 v32, vcc, s5, v36
	s_mov_b64 s[18:19], 0x2600
	s_waitcnt lgkmcnt(0)
	v_addc_co_u32_e32 v33, vcc, 0, v37, vcc
	global_load_dwordx4 v[20:23], v[24:25], off offset:1536
	s_nop 0
	global_load_dwordx4 v[24:27], v[24:25], off offset:2560
	s_nop 0
	global_load_dwordx4 v[28:31], v[32:33], off offset:1536
	s_nop 0
	global_load_dwordx4 v[32:35], v[32:33], off offset:2560
	v_lshl_add_u64 v[134:135], v[36:37], 0, s[18:19]
	s_mov_b64 s[18:19], 0x2a00
	v_lshl_add_u64 v[136:137], v[36:37], 0, s[18:19]
	v_mul_lo_u32 v36, v67, s21
	v_add3_u32 v169, 0, v0, v36
	v_lshlrev_b32_e32 v167, 2, v65
	s_barrier
	s_not_b32 s4, s4
	s_lshl_b32 s4, s4, 1
	v_ldexp_f32 v0, 1.0, s4
	v_lshlrev_b32_e32 v68, 3, v65
	v_mul_f32_e32 v150, 0x3fb8aa3b, v0
	v_readfirstlane_b32 s4, v3
	v_mul_u32_u24_e32 v0, 0x90, v64
	s_cmp_gt_i32 s4, 3
	s_mov_b64 s[4:5], -1
	v_lshlrev_b32_e32 v171, 1, v0
	v_lshlrev_b32_e32 v172, 1, v68
	s_waitcnt vmcnt(3)
	ds_write_b128 v169, v[20:23]
	s_waitcnt vmcnt(2)
	ds_write_b128 v169, v[24:27] offset:36864
	s_waitcnt vmcnt(1)
	ds_write_b128 v169, v[28:31] offset:9216
	s_waitcnt vmcnt(0)
	ds_write_b128 v169, v[32:35] offset:46080
	v_lshlrev_b32_e32 v38, 16, v4
	v_and_b32_e32 v39, 0xffff0000, v4
	v_lshlrev_b32_e32 v4, 16, v5
	v_and_b32_e32 v5, 0xffff0000, v5
	v_lshlrev_b32_e32 v50, 16, v16
	v_and_b32_e32 v51, 0xffff0000, v16
	v_pk_mul_f32 v[38:39], v[38:39], s[16:17] op_sel_hi:[1,0]
	v_pk_mul_f32 v[52:53], v[4:5], s[16:17] op_sel_hi:[1,0]
	v_cvt_pk_bf16_f32 v4, v38, v39
	v_pk_mul_f32 v[38:39], v[50:51], s[16:17] op_sel_hi:[1,0]
	v_sub_u32_e32 v20, v167, v66
	v_cvt_pk_bf16_f32 v16, v38, v39
	v_lshlrev_b32_e32 v38, 16, v17
	v_and_b32_e32 v39, 0xffff0000, v17
	v_pk_mul_f32 v[38:39], v[38:39], s[16:17] op_sel_hi:[1,0]
	v_cvt_f32_i32_e32 v170, v20
	v_cvt_pk_bf16_f32 v17, v38, v39
	v_lshlrev_b32_e32 v38, 16, v18
	v_and_b32_e32 v39, 0xffff0000, v18
	v_pk_mul_f32 v[38:39], v[38:39], s[16:17] op_sel_hi:[1,0]
	v_lshlrev_b32_e32 v40, 16, v6
	v_cvt_pk_bf16_f32 v18, v38, v39
	v_lshlrev_b32_e32 v38, 16, v19
	v_and_b32_e32 v39, 0xffff0000, v19
	v_pk_mul_f32 v[38:39], v[38:39], s[16:17] op_sel_hi:[1,0]
	v_and_b32_e32 v41, 0xffff0000, v6
	v_cvt_pk_bf16_f32 v19, v38, v39
	v_lshlrev_b32_e32 v38, 3, v2
	v_bfe_u32 v2, v2, 2, 2
	v_lshlrev_b32_e32 v6, 16, v7
	v_and_b32_e32 v7, 0xffff0000, v7
	v_lshlrev_b32_e32 v42, 16, v8
	v_and_b32_e32 v43, 0xffff0000, v8
	v_lshlrev_b32_e32 v8, 16, v9
	v_and_b32_e32 v9, 0xffff0000, v9
	v_lshlrev_b32_e32 v44, 16, v10
	v_and_b32_e32 v45, 0xffff0000, v10
	v_lshlrev_b32_e32 v10, 16, v11
	v_and_b32_e32 v11, 0xffff0000, v11
	v_lshlrev_b32_e32 v46, 16, v12
	v_and_b32_e32 v47, 0xffff0000, v12
	v_lshlrev_b32_e32 v12, 16, v13
	v_and_b32_e32 v13, 0xffff0000, v13
	v_lshlrev_b32_e32 v48, 16, v14
	v_and_b32_e32 v49, 0xffff0000, v14
	v_lshlrev_b32_e32 v14, 16, v15
	v_and_b32_e32 v15, 0xffff0000, v15
	v_or_b32_e32 v2, v167, v2
	v_pk_mul_f32 v[40:41], v[40:41], s[16:17] op_sel_hi:[1,0]
	v_pk_mul_f32 v[54:55], v[6:7], s[16:17] op_sel_hi:[1,0]
	v_pk_mul_f32 v[42:43], v[42:43], s[16:17] op_sel_hi:[1,0]
	v_pk_mul_f32 v[56:57], v[8:9], s[16:17] op_sel_hi:[1,0]
	v_pk_mul_f32 v[44:45], v[44:45], s[16:17] op_sel_hi:[1,0]
	v_pk_mul_f32 v[58:59], v[10:11], s[16:17] op_sel_hi:[1,0]
	v_pk_mul_f32 v[46:47], v[46:47], s[16:17] op_sel_hi:[1,0]
	v_pk_mul_f32 v[60:61], v[12:13], s[16:17] op_sel_hi:[1,0]
	v_pk_mul_f32 v[48:49], v[48:49], s[16:17] op_sel_hi:[1,0]
	v_pk_mul_f32 v[62:63], v[14:15], s[16:17] op_sel_hi:[1,0]
	v_and_b32_e32 v3, 24, v38
	v_mad_u32_u24 v2, v2, s21, 0
	v_cvt_pk_bf16_f32 v5, v52, v53
	v_cvt_pk_bf16_f32 v6, v40, v41
	v_cvt_pk_bf16_f32 v7, v54, v55
	v_cvt_pk_bf16_f32 v8, v42, v43
	v_cvt_pk_bf16_f32 v9, v56, v57
	v_cvt_pk_bf16_f32 v10, v44, v45
	v_cvt_pk_bf16_f32 v11, v58, v59
	v_cvt_pk_bf16_f32 v12, v46, v47
	v_cvt_pk_bf16_f32 v13, v60, v61
	v_cvt_pk_bf16_f32 v14, v48, v49
	v_cvt_pk_bf16_f32 v15, v62, v63
	v_add_u32_e32 v168, v2, v3
	s_waitcnt lgkmcnt(0)
	s_barrier
	s_cbranch_scc0 .Ld_groupA
	v_mov_b32_e32 v28, 0
	v_mov_b32_e32 v29, 0
	v_mov_b32_e32 v30, 0
	v_mov_b32_e32 v31, 0
	v_mov_b32_e32 v32, 0
	v_mov_b32_e32 v33, 0
	v_mov_b32_e32 v34, 0
	v_mov_b32_e32 v35, 0
	v_mov_b32_e32 v40, 0
	v_mov_b32_e32 v41, 0
	v_mov_b32_e32 v42, 0
	v_mov_b32_e32 v43, 0
	v_mov_b32_e32 v52, 0
	v_mov_b32_e32 v53, 0
	v_mov_b32_e32 v54, 0
	v_mov_b32_e32 v55, 0
	v_mov_b32_e32 v56, 0
	v_mov_b32_e32 v57, 0
	v_mov_b32_e32 v58, 0
	v_mov_b32_e32 v59, 0
	v_mov_b32_e32 v64, 0
	v_mov_b32_e32 v65, 0
	v_mov_b32_e32 v66, 0
	v_mov_b32_e32 v67, 0
	v_mov_b32_e32 v72, 0
	v_mov_b32_e32 v73, 0
	v_mov_b32_e32 v74, 0
	v_mov_b32_e32 v75, 0
	v_mov_b32_e32 v84, 0
	v_mov_b32_e32 v85, 0
	v_mov_b32_e32 v86, 0
	v_mov_b32_e32 v87, 0
	v_mov_b32_e32 v36, 0
	v_mov_b32_e32 v37, 0
	v_mov_b32_e32 v38, 0
	v_mov_b32_e32 v39, 0
	v_mov_b32_e32 v44, 0
	v_mov_b32_e32 v45, 0
	v_mov_b32_e32 v46, 0
	v_mov_b32_e32 v47, 0
	v_mov_b32_e32 v48, 0
	v_mov_b32_e32 v49, 0
	v_mov_b32_e32 v50, 0
	v_mov_b32_e32 v51, 0
	v_mov_b32_e32 v60, 0
	v_mov_b32_e32 v61, 0
	v_mov_b32_e32 v62, 0
	v_mov_b32_e32 v63, 0
	v_mov_b32_e32 v68, 0
	v_mov_b32_e32 v69, 0
	v_mov_b32_e32 v70, 0
	v_mov_b32_e32 v71, 0
	v_mov_b32_e32 v76, 0
	v_mov_b32_e32 v77, 0
	v_mov_b32_e32 v78, 0
	v_mov_b32_e32 v79, 0
	v_mov_b32_e32 v80, 0
	v_mov_b32_e32 v81, 0
	v_mov_b32_e32 v82, 0
	v_mov_b32_e32 v83, 0
	v_mov_b32_e32 v20, 0
	v_mov_b32_e32 v21, 0
	v_mov_b32_e32 v22, 0
	v_mov_b32_e32 v23, 0
	v_mov_b32_e32 v120, 0
	v_mov_b32_e32 v121, 0
	v_mov_b32_e32 v122, 0
	v_mov_b32_e32 v123, 0
	v_mov_b32_e32 v124, 0
	v_mov_b32_e32 v125, 0
	v_mov_b32_e32 v126, 0
	v_mov_b32_e32 v127, 0
	v_mov_b32_e32 v128, 0
	v_mov_b32_e32 v129, 0
	v_mov_b32_e32 v130, 0
	v_mov_b32_e32 v131, 0
	v_mov_b32_e32 v152, 0
	v_mov_b32_e32 v153, 0
	v_mov_b32_e32 v154, 0
	v_mov_b32_e32 v155, 0
	v_mov_b32_e32 v0, 0
	v_mov_b32_e32 v151, 0
	v_mov_b32_e32 v24, 0
	v_mov_b32_e32 v25, 0
	s_mov_b32 s66, 0xff800000
	v_add_u32_e32 v255, v171, v172
	v_mov_b32_e32 v165, v170
	s_mov_b32 s5, 0
	s_mov_b32 s31, 0
	s_mov_b32 s38, 0
	s_mov_b32 s39, 0x4800
	s_mov_b32 s30, 0xf8000
	v_mov_b32_e32 v88, 0xff800000
	v_mov_b32_e32 v89, 0xff800000
	v_mov_b32_e32 v90, 0xff800000
	v_mov_b32_e32 v91, 0xff800000
	v_mov_b32_e32 v92, 0xff800000
	v_mov_b32_e32 v93, 0xff800000
	v_mov_b32_e32 v94, 0xff800000
	v_mov_b32_e32 v95, 0xff800000
	v_mov_b32_e32 v96, 0xff800000
	v_mov_b32_e32 v97, 0xff800000
	v_mov_b32_e32 v98, 0xff800000
	v_mov_b32_e32 v99, 0xff800000
	v_mov_b32_e32 v100, 0xff800000
	v_mov_b32_e32 v101, 0xff800000
	v_mov_b32_e32 v102, 0xff800000
	v_mov_b32_e32 v103, 0xff800000
	v_mov_b32_e32 v104, 0xff800000
	v_mov_b32_e32 v105, 0xff800000
	v_mov_b32_e32 v106, 0xff800000
	v_mov_b32_e32 v107, 0xff800000
	v_mov_b32_e32 v108, 0xff800000
	v_mov_b32_e32 v109, 0xff800000
	v_mov_b32_e32 v110, 0xff800000
	v_mov_b32_e32 v111, 0xff800000
	v_mov_b32_e32 v112, 0xff800000
	v_mov_b32_e32 v113, 0xff800000
	v_mov_b32_e32 v114, 0xff800000
	v_mov_b32_e32 v115, 0xff800000
	v_mov_b32_e32 v116, 0xff800000
	v_mov_b32_e32 v117, 0xff800000
	v_mov_b32_e32 v118, 0xff800000
	v_mov_b32_e32 v119, 0xff800000
.Ld_loopB:
	s_and_b32 s8, s5, 1
	s_mul_i32 s4, s8, 0x4800
	s_xor_b32 s8, s8, 1
	s_mul_i32 s8, s8, 0x4800
	v_add_u32_e32 v173, s4, v255
	v_add_u32_e32 v175, s8, v169
	v_add_u32_e32 v174, s31, v168
	v_add_u32_e32 v203, s38, v168
	v_add_u32_e32 v164, s39, v169
	s_mov_b32 s19, 0
	s_mov_b32 s18, s30
	v_lshl_add_u64 v[212:213], v[134:135], 0, s[18:19]
	v_lshl_add_u64 v[220:221], v[136:137], 0, s[18:19]
	s_add_u32 s18, s30, 0x7c000
	v_lshl_add_u64 v[216:217], v[134:135], 0, s[18:19]
	v_lshl_add_u64 v[224:225], v[136:137], 0, s[18:19]
	global_load_dwordx4 v[212:215], v[212:213], off
	global_load_dwordx4 v[220:223], v[220:221], off
	global_load_dwordx4 v[216:219], v[216:217], off
	global_load_dwordx4 v[224:227], v[224:225], off
	ds_read_b128 v[228:231], v173 offset:0
	ds_read_b128 v[232:235], v173 offset:64
	ds_read_b128 v[236:239], v173 offset:4608
	ds_read_b128 v[240:243], v173 offset:4672
	v_max3_f32 v26, v88, v89, v90
	v_max3_f32 v26, v26, v91, v92
	v_max3_f32 v26, v26, v93, v94
	v_max3_f32 v26, v26, v95, v96
	v_max3_f32 v26, v26, v97, v98
	v_max3_f32 v26, v26, v99, v100
	v_max3_f32 v26, v26, v101, v102
	v_max_f32_e32 v26, v26, v103
	v_cmp_lt_f32_e32 vcc, s66, v26
	s_cbranch_vccz .Ld_nr_B_0
	v_mov_b32_e32 v27, v26
	s_nop 1
	v_permlane16_swap_b32_e32 v26, v27
	v_max_f32_e32 v26, v26, v27
	v_mov_b32_e32 v27, v26
	s_nop 1
	v_permlane32_swap_b32_e32 v26, v27
	v_max_f32_e32 v26, v26, v27
	v_cmp_lt_f32_e32 vcc, s66, v26
	s_nop 1
	v_cndmask_b32_e32 v2, 0, v26, vcc
	v_sub_f32_e32 v3, 0, v2
	v_min_f32_e32 v3, 0, v3
	v_exp_f32_e32 v3, v3
	v_sub_f32_e32 v24, v24, v2
	v_mul_f32_e32 v0, v0, v3
	v_mul_f32_e32 v28, v28, v3
	v_mul_f32_e32 v29, v29, v3
	v_mul_f32_e32 v30, v30, v3
	v_mul_f32_e32 v31, v31, v3
	v_mul_f32_e32 v32, v32, v3
	v_mul_f32_e32 v33, v33, v3
	v_mul_f32_e32 v34, v34, v3
	v_mul_f32_e32 v35, v35, v3
	v_mul_f32_e32 v40, v40, v3
	v_mul_f32_e32 v41, v41, v3
	v_mul_f32_e32 v42, v42, v3
	v_mul_f32_e32 v43, v43, v3
	v_mul_f32_e32 v52, v52, v3
	v_mul_f32_e32 v53, v53, v3
	v_mul_f32_e32 v54, v54, v3
	v_mul_f32_e32 v55, v55, v3
	v_mul_f32_e32 v56, v56, v3
	v_mul_f32_e32 v57, v57, v3
	v_mul_f32_e32 v58, v58, v3
	v_mul_f32_e32 v59, v59, v3
	v_mul_f32_e32 v64, v64, v3
	v_mul_f32_e32 v65, v65, v3
	v_mul_f32_e32 v66, v66, v3
	v_mul_f32_e32 v67, v67, v3
	v_mul_f32_e32 v72, v72, v3
	v_mul_f32_e32 v73, v73, v3
	v_mul_f32_e32 v74, v74, v3
	v_mul_f32_e32 v75, v75, v3
	v_mul_f32_e32 v84, v84, v3
	v_mul_f32_e32 v85, v85, v3
	v_mul_f32_e32 v86, v86, v3
	v_mul_f32_e32 v87, v87, v3
	v_sub_f32_e32 v88, v88, v2
	v_sub_f32_e32 v89, v89, v2
	v_sub_f32_e32 v90, v90, v2
	v_sub_f32_e32 v91, v91, v2
	v_sub_f32_e32 v92, v92, v2
	v_sub_f32_e32 v93, v93, v2
	v_sub_f32_e32 v94, v94, v2
	v_sub_f32_e32 v95, v95, v2
	v_sub_f32_e32 v96, v96, v2
	v_sub_f32_e32 v97, v97, v2
	v_sub_f32_e32 v98, v98, v2
	v_sub_f32_e32 v99, v99, v2
	v_sub_f32_e32 v100, v100, v2
	v_sub_f32_e32 v101, v101, v2
	v_sub_f32_e32 v102, v102, v2
	v_sub_f32_e32 v103, v103, v2
.Ld_nr_B_0:
	v_exp_f32_e32 v88, v88
	v_exp_f32_e32 v89, v89
	v_exp_f32_e32 v90, v90
	v_exp_f32_e32 v91, v91
	v_exp_f32_e32 v92, v92
	v_exp_f32_e32 v93, v93
	v_exp_f32_e32 v94, v94
	v_exp_f32_e32 v95, v95
	v_exp_f32_e32 v96, v96
	v_exp_f32_e32 v97, v97
	v_exp_f32_e32 v98, v98
	v_exp_f32_e32 v99, v99
	v_exp_f32_e32 v100, v100
	v_exp_f32_e32 v101, v101
	v_exp_f32_e32 v102, v102
	v_exp_f32_e32 v103, v103
	s_nop 0
	v_add_f32_e32 v26, v88, v89
	v_add_f32_e32 v26, v26, v90
	v_add_f32_e32 v26, v26, v91
	v_add_f32_e32 v26, v26, v92
	v_add_f32_e32 v26, v26, v93
	v_add_f32_e32 v26, v26, v94
	v_add_f32_e32 v26, v26, v95
	v_add_f32_e32 v26, v26, v96
	v_add_f32_e32 v26, v26, v97
	v_add_f32_e32 v26, v26, v98
	v_add_f32_e32 v26, v26, v99
	v_add_f32_e32 v26, v26, v100
	v_add_f32_e32 v26, v26, v101
	v_add_f32_e32 v26, v26, v102
	v_add_f32_e32 v26, v26, v103
	v_add_f32_e32 v0, v0, v26
	v_cvt_pk_bf16_f32 v120, v88, v89
	v_cvt_pk_bf16_f32 v121, v90, v91
	v_cvt_pk_bf16_f32 v122, v92, v93
	v_cvt_pk_bf16_f32 v123, v94, v95
	v_cvt_pk_bf16_f32 v124, v96, v97
	v_cvt_pk_bf16_f32 v125, v98, v99
	v_cvt_pk_bf16_f32 v126, v100, v101
	v_cvt_pk_bf16_f32 v127, v102, v103
	v_max3_f32 v26, v104, v105, v106
	v_max3_f32 v26, v26, v107, v108
	v_max3_f32 v26, v26, v109, v110
	v_max3_f32 v26, v26, v111, v112
	v_max3_f32 v26, v26, v113, v114
	v_max3_f32 v26, v26, v115, v116
	v_max3_f32 v26, v26, v117, v118
	v_max_f32_e32 v26, v26, v119
	v_cmp_lt_f32_e32 vcc, s66, v26
	s_cbranch_vccz .Ld_nr_B_1
	v_mov_b32_e32 v27, v26
	s_nop 1
	v_permlane16_swap_b32_e32 v26, v27
	v_max_f32_e32 v26, v26, v27
	v_mov_b32_e32 v27, v26
	s_nop 1
	v_permlane32_swap_b32_e32 v26, v27
	v_max_f32_e32 v26, v26, v27
	v_cmp_lt_f32_e32 vcc, s66, v26
	s_nop 1
	v_cndmask_b32_e32 v2, 0, v26, vcc
	v_sub_f32_e32 v3, 0, v2
	v_min_f32_e32 v3, 0, v3
	v_exp_f32_e32 v3, v3
	v_sub_f32_e32 v25, v25, v2
	v_mul_f32_e32 v151, v151, v3
	v_mul_f32_e32 v36, v36, v3
	v_mul_f32_e32 v37, v37, v3
	v_mul_f32_e32 v38, v38, v3
	v_mul_f32_e32 v39, v39, v3
	v_mul_f32_e32 v44, v44, v3
	v_mul_f32_e32 v45, v45, v3
	v_mul_f32_e32 v46, v46, v3
	v_mul_f32_e32 v47, v47, v3
	v_mul_f32_e32 v48, v48, v3
	v_mul_f32_e32 v49, v49, v3
	v_mul_f32_e32 v50, v50, v3
	v_mul_f32_e32 v51, v51, v3
	v_mul_f32_e32 v60, v60, v3
	v_mul_f32_e32 v61, v61, v3
	v_mul_f32_e32 v62, v62, v3
	v_mul_f32_e32 v63, v63, v3
	v_mul_f32_e32 v68, v68, v3
	v_mul_f32_e32 v69, v69, v3
	v_mul_f32_e32 v70, v70, v3
	v_mul_f32_e32 v71, v71, v3
	v_mul_f32_e32 v76, v76, v3
	v_mul_f32_e32 v77, v77, v3
	v_mul_f32_e32 v78, v78, v3
	v_mul_f32_e32 v79, v79, v3
	v_mul_f32_e32 v80, v80, v3
	v_mul_f32_e32 v81, v81, v3
	v_mul_f32_e32 v82, v82, v3
	v_mul_f32_e32 v83, v83, v3
	v_mul_f32_e32 v20, v20, v3
	v_mul_f32_e32 v21, v21, v3
	v_mul_f32_e32 v22, v22, v3
	v_mul_f32_e32 v23, v23, v3
	v_sub_f32_e32 v104, v104, v2
	v_sub_f32_e32 v105, v105, v2
	v_sub_f32_e32 v106, v106, v2
	v_sub_f32_e32 v107, v107, v2
	v_sub_f32_e32 v108, v108, v2
	v_sub_f32_e32 v109, v109, v2
	v_sub_f32_e32 v110, v110, v2
	v_sub_f32_e32 v111, v111, v2
	v_sub_f32_e32 v112, v112, v2
	v_sub_f32_e32 v113, v113, v2
	v_sub_f32_e32 v114, v114, v2
	v_sub_f32_e32 v115, v115, v2
	v_sub_f32_e32 v116, v116, v2
	v_sub_f32_e32 v117, v117, v2
	v_sub_f32_e32 v118, v118, v2
	v_sub_f32_e32 v119, v119, v2
.Ld_nr_B_1:
	v_exp_f32_e32 v104, v104
	v_exp_f32_e32 v105, v105
	v_exp_f32_e32 v106, v106
	v_exp_f32_e32 v107, v107
	v_exp_f32_e32 v108, v108
	v_exp_f32_e32 v109, v109
	v_exp_f32_e32 v110, v110
	v_exp_f32_e32 v111, v111
	v_exp_f32_e32 v112, v112
	v_exp_f32_e32 v113, v113
	v_exp_f32_e32 v114, v114
	v_exp_f32_e32 v115, v115
	v_exp_f32_e32 v116, v116
	v_exp_f32_e32 v117, v117
	v_exp_f32_e32 v118, v118
	v_exp_f32_e32 v119, v119
	s_nop 0
	v_add_f32_e32 v26, v104, v105
	v_add_f32_e32 v26, v26, v106
	v_add_f32_e32 v26, v26, v107
	v_add_f32_e32 v26, v26, v108
	v_add_f32_e32 v26, v26, v109
	v_add_f32_e32 v26, v26, v110
	v_add_f32_e32 v26, v26, v111
	v_add_f32_e32 v26, v26, v112
	v_add_f32_e32 v26, v26, v113
	v_add_f32_e32 v26, v26, v114
	v_add_f32_e32 v26, v26, v115
	v_add_f32_e32 v26, v26, v116
	v_add_f32_e32 v26, v26, v117
	v_add_f32_e32 v26, v26, v118
	v_add_f32_e32 v26, v26, v119
	v_add_f32_e32 v151, v151, v26
	v_cvt_pk_bf16_f32 v128, v104, v105
	v_cvt_pk_bf16_f32 v129, v106, v107
	v_cvt_pk_bf16_f32 v130, v108, v109
	v_cvt_pk_bf16_f32 v131, v110, v111
	v_cvt_pk_bf16_f32 v152, v112, v113
	v_cvt_pk_bf16_f32 v153, v114, v115
	v_cvt_pk_bf16_f32 v154, v116, v117
	v_cvt_pk_bf16_f32 v155, v118, v119
	v_mov_b32_e32 v156, v165
	v_add_f32_e32 v157, 0x3f800000, v165
	v_add_f32_e32 v158, 0x40000000, v165
	v_add_f32_e32 v159, 0x40400000, v165
	v_add_f32_e32 v160, 0x41800000, v165
	v_add_f32_e32 v161, 0x41880000, v165
	v_add_f32_e32 v162, 0x41900000, v165
	v_add_f32_e32 v163, 0x41980000, v165
	v_add_f32_e32 v176, 0x42000000, v165
	v_add_f32_e32 v177, 0x42040000, v165
	v_add_f32_e32 v178, 0x42080000, v165
	v_add_f32_e32 v179, 0x420c0000, v165
	v_add_f32_e32 v180, 0x42400000, v165
	v_add_f32_e32 v181, 0x42440000, v165
	v_add_f32_e32 v182, 0x42480000, v165
	v_add_f32_e32 v183, 0x424c0000, v165
	v_fma_f32 v204, -v150, |v156|, v25
	v_fma_f32 v205, -v150, |v157|, v25
	v_fma_f32 v206, -v150, |v158|, v25
	v_fma_f32 v207, -v150, |v159|, v25
	v_fma_f32 v208, -v150, |v160|, v25
	v_fma_f32 v209, -v150, |v161|, v25
	v_fma_f32 v210, -v150, |v162|, v25
	v_fma_f32 v211, -v150, |v163|, v25
	v_fma_f32 v184, -v150, |v176|, v25
	v_fma_f32 v185, -v150, |v177|, v25
	v_fma_f32 v186, -v150, |v178|, v25
	v_fma_f32 v187, -v150, |v179|, v25
	v_fma_f32 v188, -v150, |v180|, v25
	v_fma_f32 v189, -v150, |v181|, v25
	v_fma_f32 v190, -v150, |v182|, v25
	v_fma_f32 v191, -v150, |v183|, v25
	v_fma_f32 v156, -v150, |v156|, v24
	v_fma_f32 v157, -v150, |v157|, v24
	v_fma_f32 v158, -v150, |v158|, v24
	v_fma_f32 v159, -v150, |v159|, v24
	v_fma_f32 v160, -v150, |v160|, v24
	v_fma_f32 v161, -v150, |v161|, v24
	v_fma_f32 v162, -v150, |v162|, v24
	v_fma_f32 v163, -v150, |v163|, v24
	v_fma_f32 v176, -v150, |v176|, v24
	v_fma_f32 v177, -v150, |v177|, v24
	v_fma_f32 v178, -v150, |v178|, v24
	v_fma_f32 v179, -v150, |v179|, v24
	v_fma_f32 v180, -v150, |v180|, v24
	v_fma_f32 v181, -v150, |v181|, v24
	v_fma_f32 v182, -v150, |v182|, v24
	v_fma_f32 v183, -v150, |v183|, v24
	ds_read_b128 v[244:247], v173 offset:9216
	s_waitcnt lgkmcnt(4)
	v_mfma_f32_16x16x32_bf16 v[88:91], v[228:231], v[4:7], v[156:159]
	ds_read_b128 v[248:251], v173 offset:9280
	s_waitcnt lgkmcnt(4)
	v_mfma_f32_16x16x32_bf16 v[88:91], v[232:235], v[8:11], v[88:91]
	ds_read_b128 v[228:231], v173 offset:13824
	s_waitcnt lgkmcnt(4)
	v_mfma_f32_16x16x32_bf16 v[92:95], v[236:239], v[4:7], v[160:163]
	ds_read_b128 v[232:235], v173 offset:13888
	s_waitcnt lgkmcnt(4)
	v_mfma_f32_16x16x32_bf16 v[92:95], v[240:243], v[8:11], v[92:95]
	ds_read_b128 v[236:239], v173 offset:128
	s_waitcnt lgkmcnt(4)
	v_mfma_f32_16x16x32_bf16 v[96:99], v[244:247], v[4:7], v[176:179]
	ds_read_b128 v[240:243], v173 offset:192
	s_waitcnt lgkmcnt(4)
	v_mfma_f32_16x16x32_bf16 v[96:99], v[248:251], v[8:11], v[96:99]
	ds_read_b128 v[244:247], v173 offset:4736
	s_waitcnt lgkmcnt(4)
	v_mfma_f32_16x16x32_bf16 v[100:103], v[228:231], v[4:7], v[180:183]
	ds_read_b128 v[248:251], v173 offset:4800
	s_waitcnt lgkmcnt(4)
	v_mfma_f32_16x16x32_bf16 v[100:103], v[232:235], v[8:11], v[100:103]
	ds_read_b128 v[228:231], v173 offset:9344
	s_waitcnt lgkmcnt(4)
	v_mfma_f32_16x16x32_bf16 v[104:107], v[236:239], v[12:15], v[204:207]
	ds_read_b128 v[232:235], v173 offset:9408
	s_waitcnt lgkmcnt(4)
	v_mfma_f32_16x16x32_bf16 v[104:107], v[240:243], v[16:19], v[104:107]
	ds_read_b128 v[236:239], v173 offset:13952
	s_waitcnt lgkmcnt(4)
	v_mfma_f32_16x16x32_bf16 v[108:111], v[244:247], v[12:15], v[208:211]
	ds_read_b128 v[240:243], v173 offset:14016
	s_waitcnt lgkmcnt(4)
	v_mfma_f32_16x16x32_bf16 v[108:111], v[248:251], v[16:19], v[108:111]
	ds_read_b64_tr_b16 v[244:245], v174 offset:36864
	ds_read_b64_tr_b16 v[246:247], v174 offset:41472
	s_waitcnt lgkmcnt(5)
	v_mfma_f32_16x16x32_bf16 v[112:115], v[228:231], v[12:15], v[184:187]
	ds_read_b64_tr_b16 v[248:249], v174 offset:36896
	ds_read_b64_tr_b16 v[250:251], v174 offset:41504
	s_waitcnt lgkmcnt(6)
	v_mfma_f32_16x16x32_bf16 v[112:115], v[232:235], v[16:19], v[112:115]
	ds_read_b64_tr_b16 v[228:229], v174 offset:36928
	ds_read_b64_tr_b16 v[230:231], v174 offset:41536
	s_waitcnt lgkmcnt(7)
	v_mfma_f32_16x16x32_bf16 v[116:119], v[236:239], v[12:15], v[188:191]
	ds_read_b64_tr_b16 v[232:233], v174 offset:36960
	ds_read_b64_tr_b16 v[234:235], v174 offset:41568
	s_waitcnt lgkmcnt(8)
	v_mfma_f32_16x16x32_bf16 v[116:119], v[240:243], v[16:19], v[116:119]
	ds_read_b64_tr_b16 v[236:237], v174 offset:36992
	ds_read_b64_tr_b16 v[238:239], v174 offset:41600
	s_waitcnt lgkmcnt(8)
	v_mfma_f32_16x16x32_bf16 v[28:31], v[244:247], v[120:123], v[28:31]
	v_mfma_f32_16x16x32_bf16 v[36:39], v[244:247], v[128:131], v[36:39]
	ds_read_b64_tr_b16 v[240:241], v174 offset:37024
	ds_read_b64_tr_b16 v[242:243], v174 offset:41632
	s_waitcnt lgkmcnt(8)
	v_mfma_f32_16x16x32_bf16 v[32:35], v[248:251], v[120:123], v[32:35]
	v_mfma_f32_16x16x32_bf16 v[44:47], v[248:251], v[128:131], v[44:47]
	ds_read_b64_tr_b16 v[244:245], v174 offset:37056
	ds_read_b64_tr_b16 v[246:247], v174 offset:41664
	s_waitcnt lgkmcnt(8)
	v_mfma_f32_16x16x32_bf16 v[40:43], v[228:231], v[120:123], v[40:43]
	v_mfma_f32_16x16x32_bf16 v[48:51], v[228:231], v[128:131], v[48:51]
	ds_read_b64_tr_b16 v[248:249], v174 offset:37088
	ds_read_b64_tr_b16 v[250:251], v174 offset:41696
	s_waitcnt lgkmcnt(8)
	v_mfma_f32_16x16x32_bf16 v[52:55], v[232:235], v[120:123], v[52:55]
	v_mfma_f32_16x16x32_bf16 v[60:63], v[232:235], v[128:131], v[60:63]
	ds_read_b64_tr_b16 v[228:229], v174 offset:46080
	ds_read_b64_tr_b16 v[230:231], v174 offset:50688
	s_waitcnt lgkmcnt(8)
	v_mfma_f32_16x16x32_bf16 v[56:59], v[236:239], v[120:123], v[56:59]
	v_mfma_f32_16x16x32_bf16 v[68:71], v[236:239], v[128:131], v[68:71]
	ds_read_b64_tr_b16 v[232:233], v174 offset:46112
	ds_read_b64_tr_b16 v[234:235], v174 offset:50720
	s_waitcnt lgkmcnt(8)
	v_mfma_f32_16x16x32_bf16 v[64:67], v[240:243], v[120:123], v[64:67]
	v_mfma_f32_16x16x32_bf16 v[76:79], v[240:243], v[128:131], v[76:79]
	ds_read_b64_tr_b16 v[236:237], v174 offset:46144
	ds_read_b64_tr_b16 v[238:239], v174 offset:50752
	s_waitcnt lgkmcnt(8)
	v_mfma_f32_16x16x32_bf16 v[72:75], v[244:247], v[120:123], v[72:75]
	v_mfma_f32_16x16x32_bf16 v[80:83], v[244:247], v[128:131], v[80:83]
	ds_read_b64_tr_b16 v[240:241], v174 offset:46176
	ds_read_b64_tr_b16 v[242:243], v174 offset:50784
	s_waitcnt lgkmcnt(8)
	v_mfma_f32_16x16x32_bf16 v[84:87], v[248:251], v[120:123], v[84:87]
	v_mfma_f32_16x16x32_bf16 v[20:23], v[248:251], v[128:131], v[20:23]
	ds_read_b64_tr_b16 v[244:245], v174 offset:46208
	ds_read_b64_tr_b16 v[246:247], v174 offset:50816
	s_waitcnt lgkmcnt(8)
	v_mfma_f32_16x16x32_bf16 v[28:31], v[228:231], v[124:127], v[28:31]
	v_mfma_f32_16x16x32_bf16 v[36:39], v[228:231], v[152:155], v[36:39]
	ds_read_b64_tr_b16 v[248:249], v174 offset:46240
	ds_read_b64_tr_b16 v[250:251], v174 offset:50848
	s_waitcnt lgkmcnt(8)
	v_mfma_f32_16x16x32_bf16 v[32:35], v[232:235], v[124:127], v[32:35]
	v_mfma_f32_16x16x32_bf16 v[44:47], v[232:235], v[152:155], v[44:47]
	ds_read_b64_tr_b16 v[228:229], v174 offset:46272
	ds_read_b64_tr_b16 v[230:231], v174 offset:50880
	s_waitcnt lgkmcnt(8)
	v_mfma_f32_16x16x32_bf16 v[40:43], v[236:239], v[124:127], v[40:43]
	v_mfma_f32_16x16x32_bf16 v[48:51], v[236:239], v[152:155], v[48:51]
	ds_read_b64_tr_b16 v[232:233], v174 offset:46304
	ds_read_b64_tr_b16 v[234:235], v174 offset:50912
	s_waitcnt lgkmcnt(8)
	v_mfma_f32_16x16x32_bf16 v[52:55], v[240:243], v[124:127], v[52:55]
	v_mfma_f32_16x16x32_bf16 v[60:63], v[240:243], v[152:155], v[60:63]
	s_waitcnt lgkmcnt(6)
	v_mfma_f32_16x16x32_bf16 v[56:59], v[244:247], v[124:127], v[56:59]
	v_mfma_f32_16x16x32_bf16 v[68:71], v[244:247], v[152:155], v[68:71]
	s_waitcnt lgkmcnt(4)
	v_mfma_f32_16x16x32_bf16 v[64:67], v[248:251], v[124:127], v[64:67]
	v_mfma_f32_16x16x32_bf16 v[76:79], v[248:251], v[152:155], v[76:79]
	s_waitcnt lgkmcnt(2)
	v_mfma_f32_16x16x32_bf16 v[72:75], v[228:231], v[124:127], v[72:75]
	v_mfma_f32_16x16x32_bf16 v[80:83], v[228:231], v[152:155], v[80:83]
	s_waitcnt lgkmcnt(0)
	v_mfma_f32_16x16x32_bf16 v[84:87], v[232:235], v[124:127], v[84:87]
	v_mfma_f32_16x16x32_bf16 v[20:23], v[232:235], v[152:155], v[20:23]
	s_waitcnt vmcnt(0)
	ds_write_b128 v175, v[212:215]
	ds_write_b128 v175, v[216:219] offset:9216
	ds_write_b128 v164, v[220:223] offset:36864
	ds_write_b128 v164, v[224:227] offset:46080
	s_mov_b32 s31, s38
	s_mov_b32 s38, s39
	s_add_i32 s39, s39, 0x4800
	s_cmp_lg_u32 s39, 0xd800
	s_cselect_b32 s39, s39, 0
	s_mov_b32 s66, 0xff800000
	s_cmp_ge_u32 s5, 1
	s_cselect_b32 s66, 0x41000000, s66
	s_add_i32 s5, s5, 1
	s_min_u32 s8, s5, 62
	s_add_i32 s8, s8, 1
	s_mul_i32 s30, s8, 0xf8000
	v_add_f32_e32 v165, 0x42800000, v165
	s_waitcnt lgkmcnt(0)
	s_barrier
	s_cmp_lt_u32 s5, 64
	s_cbranch_scc1 .Ld_loopB
	v_add_u32_e32 v174, s31, v168
	ds_read_b64_tr_b16 v[228:229], v174 offset:36864
	ds_read_b64_tr_b16 v[230:231], v174 offset:41472
	ds_read_b64_tr_b16 v[232:233], v174 offset:36896
	ds_read_b64_tr_b16 v[234:235], v174 offset:41504
	ds_read_b64_tr_b16 v[236:237], v174 offset:36928
	ds_read_b64_tr_b16 v[238:239], v174 offset:41536
	ds_read_b64_tr_b16 v[240:241], v174 offset:36960
	ds_read_b64_tr_b16 v[242:243], v174 offset:41568
	v_max3_f32 v26, v88, v89, v90
	v_max3_f32 v26, v26, v91, v92
	v_max3_f32 v26, v26, v93, v94
	v_max3_f32 v26, v26, v95, v96
	v_max3_f32 v26, v26, v97, v98
	v_max3_f32 v26, v26, v99, v100
	v_max3_f32 v26, v26, v101, v102
	v_max_f32_e32 v26, v26, v103
	v_cmp_lt_f32_e32 vcc, s66, v26
	s_cbranch_vccz .Ld_nr_Bt_0
	v_mov_b32_e32 v27, v26
	s_nop 1
	v_permlane16_swap_b32_e32 v26, v27
	v_max_f32_e32 v26, v26, v27
	v_mov_b32_e32 v27, v26
	s_nop 1
	v_permlane32_swap_b32_e32 v26, v27
	v_max_f32_e32 v26, v26, v27
	v_cmp_lt_f32_e32 vcc, s66, v26
	s_nop 1
	v_cndmask_b32_e32 v2, 0, v26, vcc
	v_sub_f32_e32 v3, 0, v2
	v_min_f32_e32 v3, 0, v3
	v_exp_f32_e32 v3, v3
	v_sub_f32_e32 v24, v24, v2
	v_mul_f32_e32 v0, v0, v3
	v_mul_f32_e32 v28, v28, v3
	v_mul_f32_e32 v29, v29, v3
	v_mul_f32_e32 v30, v30, v3
	v_mul_f32_e32 v31, v31, v3
	v_mul_f32_e32 v32, v32, v3
	v_mul_f32_e32 v33, v33, v3
	v_mul_f32_e32 v34, v34, v3
	v_mul_f32_e32 v35, v35, v3
	v_mul_f32_e32 v40, v40, v3
	v_mul_f32_e32 v41, v41, v3
	v_mul_f32_e32 v42, v42, v3
	v_mul_f32_e32 v43, v43, v3
	v_mul_f32_e32 v52, v52, v3
	v_mul_f32_e32 v53, v53, v3
	v_mul_f32_e32 v54, v54, v3
	v_mul_f32_e32 v55, v55, v3
	v_mul_f32_e32 v56, v56, v3
	v_mul_f32_e32 v57, v57, v3
	v_mul_f32_e32 v58, v58, v3
	v_mul_f32_e32 v59, v59, v3
	v_mul_f32_e32 v64, v64, v3
	v_mul_f32_e32 v65, v65, v3
	v_mul_f32_e32 v66, v66, v3
	v_mul_f32_e32 v67, v67, v3
	v_mul_f32_e32 v72, v72, v3
	v_mul_f32_e32 v73, v73, v3
	v_mul_f32_e32 v74, v74, v3
	v_mul_f32_e32 v75, v75, v3
	v_mul_f32_e32 v84, v84, v3
	v_mul_f32_e32 v85, v85, v3
	v_mul_f32_e32 v86, v86, v3
	v_mul_f32_e32 v87, v87, v3
	v_sub_f32_e32 v88, v88, v2
	v_sub_f32_e32 v89, v89, v2
	v_sub_f32_e32 v90, v90, v2
	v_sub_f32_e32 v91, v91, v2
	v_sub_f32_e32 v92, v92, v2
	v_sub_f32_e32 v93, v93, v2
	v_sub_f32_e32 v94, v94, v2
	v_sub_f32_e32 v95, v95, v2
	v_sub_f32_e32 v96, v96, v2
	v_sub_f32_e32 v97, v97, v2
	v_sub_f32_e32 v98, v98, v2
	v_sub_f32_e32 v99, v99, v2
	v_sub_f32_e32 v100, v100, v2
	v_sub_f32_e32 v101, v101, v2
	v_sub_f32_e32 v102, v102, v2
	v_sub_f32_e32 v103, v103, v2

.Ld_nr_Bt_1:
	v_exp_f32_e32 v104, v104
	v_exp_f32_e32 v105, v105
	v_exp_f32_e32 v106, v106
	v_exp_f32_e32 v107, v107
	v_exp_f32_e32 v108, v108
	v_exp_f32_e32 v109, v109
	v_exp_f32_e32 v110, v110
	v_exp_f32_e32 v111, v111
	v_exp_f32_e32 v112, v112
	v_exp_f32_e32 v113, v113
	v_exp_f32_e32 v114, v114
	v_exp_f32_e32 v115, v115
	v_exp_f32_e32 v116, v116
	v_exp_f32_e32 v117, v117
	v_exp_f32_e32 v118, v118
	v_exp_f32_e32 v119, v119
	s_nop 0
	v_add_f32_e32 v26, v104, v105
	v_add_f32_e32 v26, v26, v106
	v_add_f32_e32 v26, v26, v107
	v_add_f32_e32 v26, v26, v108
	v_add_f32_e32 v26, v26, v109
	v_add_f32_e32 v26, v26, v110
	v_add_f32_e32 v26, v26, v111
	v_add_f32_e32 v26, v26, v112
	v_add_f32_e32 v26, v26, v113
	v_add_f32_e32 v26, v26, v114
	v_add_f32_e32 v26, v26, v115
	v_add_f32_e32 v26, v26, v116
	v_add_f32_e32 v26, v26, v117
	v_add_f32_e32 v26, v26, v118
	v_add_f32_e32 v26, v26, v119
	v_add_f32_e32 v151, v151, v26
	v_cvt_pk_bf16_f32 v128, v104, v105
	v_cvt_pk_bf16_f32 v129, v106, v107
	v_cvt_pk_bf16_f32 v130, v108, v109
	v_cvt_pk_bf16_f32 v131, v110, v111
	v_cvt_pk_bf16_f32 v152, v112, v113
	v_cvt_pk_bf16_f32 v153, v114, v115
	v_cvt_pk_bf16_f32 v154, v116, v117
	v_cvt_pk_bf16_f32 v155, v118, v119
	ds_read_b64_tr_b16 v[244:245], v174 offset:36992
	ds_read_b64_tr_b16 v[246:247], v174 offset:41600
	s_waitcnt lgkmcnt(8)
	v_mfma_f32_16x16x32_bf16 v[28:31], v[228:231], v[120:123], v[28:31]
	v_mfma_f32_16x16x32_bf16 v[36:39], v[228:231], v[128:131], v[36:39]
	ds_read_b64_tr_b16 v[248:249], v174 offset:37024
	ds_read_b64_tr_b16 v[250:251], v174 offset:41632
	s_waitcnt lgkmcnt(8)
	v_mfma_f32_16x16x32_bf16 v[32:35], v[232:235], v[120:123], v[32:35]
	v_mfma_f32_16x16x32_bf16 v[44:47], v[232:235], v[128:131], v[44:47]
	ds_read_b64_tr_b16 v[228:229], v174 offset:37056
	ds_read_b64_tr_b16 v[230:231], v174 offset:41664
	s_waitcnt lgkmcnt(8)
	v_mfma_f32_16x16x32_bf16 v[40:43], v[236:239], v[120:123], v[40:43]
	v_mfma_f32_16x16x32_bf16 v[48:51], v[236:239], v[128:131], v[48:51]
	ds_read_b64_tr_b16 v[232:233], v174 offset:37088
	ds_read_b64_tr_b16 v[234:235], v174 offset:41696
	s_waitcnt lgkmcnt(8)
	v_mfma_f32_16x16x32_bf16 v[52:55], v[240:243], v[120:123], v[52:55]
	v_mfma_f32_16x16x32_bf16 v[60:63], v[240:243], v[128:131], v[60:63]
	ds_read_b64_tr_b16 v[236:237], v174 offset:46080
	ds_read_b64_tr_b16 v[238:239], v174 offset:50688
	s_waitcnt lgkmcnt(8)
	v_mfma_f32_16x16x32_bf16 v[56:59], v[244:247], v[120:123], v[56:59]
	v_mfma_f32_16x16x32_bf16 v[68:71], v[244:247], v[128:131], v[68:71]
	ds_read_b64_tr_b16 v[240:241], v174 offset:46112
	ds_read_b64_tr_b16 v[242:243], v174 offset:50720
	s_waitcnt lgkmcnt(8)
	v_mfma_f32_16x16x32_bf16 v[64:67], v[248:251], v[120:123], v[64:67]
	v_mfma_f32_16x16x32_bf16 v[76:79], v[248:251], v[128:131], v[76:79]
	ds_read_b64_tr_b16 v[244:245], v174 offset:46144
	ds_read_b64_tr_b16 v[246:247], v174 offset:50752
	s_waitcnt lgkmcnt(8)
	v_mfma_f32_16x16x32_bf16 v[72:75], v[228:231], v[120:123], v[72:75]
	v_mfma_f32_16x16x32_bf16 v[80:83], v[228:231], v[128:131], v[80:83]
	ds_read_b64_tr_b16 v[248:249], v174 offset:46176
	ds_read_b64_tr_b16 v[250:251], v174 offset:50784
	s_waitcnt lgkmcnt(8)
	v_mfma_f32_16x16x32_bf16 v[84:87], v[232:235], v[120:123], v[84:87]
	v_mfma_f32_16x16x32_bf16 v[20:23], v[232:235], v[128:131], v[20:23]
	ds_read_b64_tr_b16 v[228:229], v174 offset:46208
	ds_read_b64_tr_b16 v[230:231], v174 offset:50816
	s_waitcnt lgkmcnt(8)
	v_mfma_f32_16x16x32_bf16 v[28:31], v[236:239], v[124:127], v[28:31]
	v_mfma_f32_16x16x32_bf16 v[36:39], v[236:239], v[152:155], v[36:39]
	ds_read_b64_tr_b16 v[232:233], v174 offset:46240
	ds_read_b64_tr_b16 v[234:235], v174 offset:50848
	s_waitcnt lgkmcnt(8)
	v_mfma_f32_16x16x32_bf16 v[32:35], v[240:243], v[124:127], v[32:35]
	v_mfma_f32_16x16x32_bf16 v[44:47], v[240:243], v[152:155], v[44:47]
	ds_read_b64_tr_b16 v[236:237], v174 offset:46272
	ds_read_b64_tr_b16 v[238:239], v174 offset:50880
	s_waitcnt lgkmcnt(8)
	v_mfma_f32_16x16x32_bf16 v[40:43], v[244:247], v[124:127], v[40:43]
	v_mfma_f32_16x16x32_bf16 v[48:51], v[244:247], v[152:155], v[48:51]
	ds_read_b64_tr_b16 v[240:241], v174 offset:46304
	ds_read_b64_tr_b16 v[242:243], v174 offset:50912
	s_waitcnt lgkmcnt(8)
	v_mfma_f32_16x16x32_bf16 v[52:55], v[248:251], v[124:127], v[52:55]
	v_mfma_f32_16x16x32_bf16 v[60:63], v[248:251], v[152:155], v[60:63]
	s_waitcnt lgkmcnt(6)
	v_mfma_f32_16x16x32_bf16 v[56:59], v[228:231], v[124:127], v[56:59]
	v_mfma_f32_16x16x32_bf16 v[68:71], v[228:231], v[152:155], v[68:71]
	s_waitcnt lgkmcnt(4)
	v_mfma_f32_16x16x32_bf16 v[64:67], v[232:235], v[124:127], v[64:67]
	v_mfma_f32_16x16x32_bf16 v[76:79], v[232:235], v[152:155], v[76:79]
	s_waitcnt lgkmcnt(2)
	v_mfma_f32_16x16x32_bf16 v[72:75], v[236:239], v[124:127], v[72:75]
	v_mfma_f32_16x16x32_bf16 v[80:83], v[236:239], v[152:155], v[80:83]
	s_waitcnt lgkmcnt(0)
	v_mfma_f32_16x16x32_bf16 v[84:87], v[240:243], v[124:127], v[84:87]
	v_mfma_f32_16x16x32_bf16 v[20:23], v[240:243], v[152:155], v[20:23]
	s_branch .LBB0_634
.Ld_groupA:
	v_mov_b32_e32 v28, 0
	v_mov_b32_e32 v29, 0
	v_mov_b32_e32 v30, 0
	v_mov_b32_e32 v31, 0
	v_mov_b32_e32 v32, 0
	v_mov_b32_e32 v33, 0
	v_mov_b32_e32 v34, 0
	v_mov_b32_e32 v35, 0
	v_mov_b32_e32 v40, 0
	v_mov_b32_e32 v41, 0
	v_mov_b32_e32 v42, 0
	v_mov_b32_e32 v43, 0
	v_mov_b32_e32 v52, 0
	v_mov_b32_e32 v53, 0
	v_mov_b32_e32 v54, 0
	v_mov_b32_e32 v55, 0
	v_mov_b32_e32 v56, 0
	v_mov_b32_e32 v57, 0
	v_mov_b32_e32 v58, 0
	v_mov_b32_e32 v59, 0
	v_mov_b32_e32 v64, 0
	v_mov_b32_e32 v65, 0
	v_mov_b32_e32 v66, 0
	v_mov_b32_e32 v67, 0
	v_mov_b32_e32 v72, 0
	v_mov_b32_e32 v73, 0
	v_mov_b32_e32 v74, 0
	v_mov_b32_e32 v75, 0
	v_mov_b32_e32 v84, 0
	v_mov_b32_e32 v85, 0
	v_mov_b32_e32 v86, 0
	v_mov_b32_e32 v87, 0
	v_mov_b32_e32 v36, 0
	v_mov_b32_e32 v37, 0
	v_mov_b32_e32 v38, 0
	v_mov_b32_e32 v39, 0
	v_mov_b32_e32 v44, 0
	v_mov_b32_e32 v45, 0
	v_mov_b32_e32 v46, 0
	v_mov_b32_e32 v47, 0
	v_mov_b32_e32 v48, 0
	v_mov_b32_e32 v49, 0
	v_mov_b32_e32 v50, 0
	v_mov_b32_e32 v51, 0
	v_mov_b32_e32 v60, 0
	v_mov_b32_e32 v61, 0
	v_mov_b32_e32 v62, 0
	v_mov_b32_e32 v63, 0
	v_mov_b32_e32 v68, 0
	v_mov_b32_e32 v69, 0
	v_mov_b32_e32 v70, 0
	v_mov_b32_e32 v71, 0
	v_mov_b32_e32 v76, 0
	v_mov_b32_e32 v77, 0
	v_mov_b32_e32 v78, 0
	v_mov_b32_e32 v79, 0
	v_mov_b32_e32 v80, 0
	v_mov_b32_e32 v81, 0
	v_mov_b32_e32 v82, 0
	v_mov_b32_e32 v83, 0
	v_mov_b32_e32 v20, 0
	v_mov_b32_e32 v21, 0
	v_mov_b32_e32 v22, 0
	v_mov_b32_e32 v23, 0
	v_mov_b32_e32 v120, 0
	v_mov_b32_e32 v121, 0
	v_mov_b32_e32 v122, 0
	v_mov_b32_e32 v123, 0
	v_mov_b32_e32 v124, 0
	v_mov_b32_e32 v125, 0
	v_mov_b32_e32 v126, 0
	v_mov_b32_e32 v127, 0
	v_mov_b32_e32 v128, 0
	v_mov_b32_e32 v129, 0
	v_mov_b32_e32 v130, 0
	v_mov_b32_e32 v131, 0
	v_mov_b32_e32 v152, 0
	v_mov_b32_e32 v153, 0
	v_mov_b32_e32 v154, 0
	v_mov_b32_e32 v155, 0
	v_mov_b32_e32 v0, 0
	v_mov_b32_e32 v151, 0
	v_mov_b32_e32 v24, 0
	v_mov_b32_e32 v25, 0
	s_mov_b32 s66, 0xff800000
	v_add_u32_e32 v255, v171, v172
	v_mov_b32_e32 v165, v170
	s_mov_b32 s5, 0
	s_mov_b32 s31, 0
	s_mov_b32 s38, 0
	s_mov_b32 s39, 0x4800
	s_mov_b32 s30, 0xf8000
	v_mov_b32_e32 v156, v165
	v_add_f32_e32 v157, 0x3f800000, v165
	v_add_f32_e32 v158, 0x40000000, v165
	v_add_f32_e32 v159, 0x40400000, v165
	v_add_f32_e32 v160, 0x41800000, v165
	v_add_f32_e32 v161, 0x41880000, v165
	v_add_f32_e32 v162, 0x41900000, v165
	v_add_f32_e32 v163, 0x41980000, v165
	v_add_f32_e32 v176, 0x42000000, v165
	v_add_f32_e32 v177, 0x42040000, v165
	v_add_f32_e32 v178, 0x42080000, v165
	v_add_f32_e32 v179, 0x420c0000, v165
	v_add_f32_e32 v180, 0x42400000, v165
	v_add_f32_e32 v181, 0x42440000, v165
	v_add_f32_e32 v182, 0x42480000, v165
	v_add_f32_e32 v183, 0x424c0000, v165
	v_fma_f32 v204, -v150, |v156|, v25
	v_fma_f32 v205, -v150, |v157|, v25
	v_fma_f32 v206, -v150, |v158|, v25
	v_fma_f32 v207, -v150, |v159|, v25
	v_fma_f32 v208, -v150, |v160|, v25
	v_fma_f32 v209, -v150, |v161|, v25
	v_fma_f32 v210, -v150, |v162|, v25
	v_fma_f32 v211, -v150, |v163|, v25
	v_fma_f32 v184, -v150, |v176|, v25
	v_fma_f32 v185, -v150, |v177|, v25
	v_fma_f32 v186, -v150, |v178|, v25
	v_fma_f32 v187, -v150, |v179|, v25
	v_fma_f32 v188, -v150, |v180|, v25
	v_fma_f32 v189, -v150, |v181|, v25
	v_fma_f32 v190, -v150, |v182|, v25
	v_fma_f32 v191, -v150, |v183|, v25
	v_fma_f32 v156, -v150, |v156|, v24
	v_fma_f32 v157, -v150, |v157|, v24
	v_fma_f32 v158, -v150, |v158|, v24
	v_fma_f32 v159, -v150, |v159|, v24
	v_fma_f32 v160, -v150, |v160|, v24
	v_fma_f32 v161, -v150, |v161|, v24
	v_fma_f32 v162, -v150, |v162|, v24
	v_fma_f32 v163, -v150, |v163|, v24
	v_fma_f32 v176, -v150, |v176|, v24
	v_fma_f32 v177, -v150, |v177|, v24
	v_fma_f32 v178, -v150, |v178|, v24
	v_fma_f32 v179, -v150, |v179|, v24
	v_fma_f32 v180, -v150, |v180|, v24
	v_fma_f32 v181, -v150, |v181|, v24
	v_fma_f32 v182, -v150, |v182|, v24
	v_fma_f32 v183, -v150, |v183|, v24
.Ld_loopA:
	s_and_b32 s8, s5, 1
	s_mul_i32 s4, s8, 0x4800
	s_xor_b32 s8, s8, 1
	s_mul_i32 s8, s8, 0x4800
	v_add_u32_e32 v173, s4, v255
	v_add_u32_e32 v175, s8, v169
	v_add_u32_e32 v174, s31, v168
	v_add_u32_e32 v203, s38, v168
	v_add_u32_e32 v164, s39, v169
	s_mov_b32 s19, 0
	s_mov_b32 s18, s30
	v_lshl_add_u64 v[212:213], v[134:135], 0, s[18:19]
	v_lshl_add_u64 v[220:221], v[136:137], 0, s[18:19]
	s_add_u32 s18, s30, 0x7c000
	v_lshl_add_u64 v[216:217], v[134:135], 0, s[18:19]
	v_lshl_add_u64 v[224:225], v[136:137], 0, s[18:19]
	global_load_dwordx4 v[212:215], v[212:213], off
	global_load_dwordx4 v[220:223], v[220:221], off
	global_load_dwordx4 v[216:219], v[216:217], off
	global_load_dwordx4 v[224:227], v[224:225], off
	ds_read_b64_tr_b16 v[228:229], v174 offset:36864
	ds_read_b64_tr_b16 v[230:231], v174 offset:41472
	ds_read_b64_tr_b16 v[232:233], v174 offset:36896
	ds_read_b64_tr_b16 v[234:235], v174 offset:41504
	ds_read_b64_tr_b16 v[236:237], v174 offset:36928
	ds_read_b64_tr_b16 v[238:239], v174 offset:41536
	ds_read_b64_tr_b16 v[240:241], v174 offset:36960
	ds_read_b64_tr_b16 v[242:243], v174 offset:41568
	ds_read_b64_tr_b16 v[244:245], v174 offset:36992
	ds_read_b64_tr_b16 v[246:247], v174 offset:41600
	s_waitcnt lgkmcnt(8)
	v_mfma_f32_16x16x32_bf16 v[28:31], v[228:231], v[120:123], v[28:31]
	v_mfma_f32_16x16x32_bf16 v[36:39], v[228:231], v[128:131], v[36:39]
	ds_read_b64_tr_b16 v[248:249], v174 offset:37024
	ds_read_b64_tr_b16 v[250:251], v174 offset:41632
	s_waitcnt lgkmcnt(8)
	v_mfma_f32_16x16x32_bf16 v[32:35], v[232:235], v[120:123], v[32:35]
	v_mfma_f32_16x16x32_bf16 v[44:47], v[232:235], v[128:131], v[44:47]
	ds_read_b64_tr_b16 v[228:229], v174 offset:37056
	ds_read_b64_tr_b16 v[230:231], v174 offset:41664
	s_waitcnt lgkmcnt(8)
	v_mfma_f32_16x16x32_bf16 v[40:43], v[236:239], v[120:123], v[40:43]
	v_mfma_f32_16x16x32_bf16 v[48:51], v[236:239], v[128:131], v[48:51]
	ds_read_b64_tr_b16 v[232:233], v174 offset:37088
	ds_read_b64_tr_b16 v[234:235], v174 offset:41696
	s_waitcnt lgkmcnt(8)
	v_mfma_f32_16x16x32_bf16 v[52:55], v[240:243], v[120:123], v[52:55]
	v_mfma_f32_16x16x32_bf16 v[60:63], v[240:243], v[128:131], v[60:63]
	ds_read_b64_tr_b16 v[236:237], v174 offset:46080
	ds_read_b64_tr_b16 v[238:239], v174 offset:50688
	s_waitcnt lgkmcnt(8)
	v_mfma_f32_16x16x32_bf16 v[56:59], v[244:247], v[120:123], v[56:59]
	v_mfma_f32_16x16x32_bf16 v[68:71], v[244:247], v[128:131], v[68:71]
	ds_read_b64_tr_b16 v[240:241], v174 offset:46112
	ds_read_b64_tr_b16 v[242:243], v174 offset:50720
	s_waitcnt lgkmcnt(8)
	v_mfma_f32_16x16x32_bf16 v[64:67], v[248:251], v[120:123], v[64:67]
	v_mfma_f32_16x16x32_bf16 v[76:79], v[248:251], v[128:131], v[76:79]
	ds_read_b64_tr_b16 v[244:245], v174 offset:46144
	ds_read_b64_tr_b16 v[246:247], v174 offset:50752
	s_waitcnt lgkmcnt(8)
	v_mfma_f32_16x16x32_bf16 v[72:75], v[228:231], v[120:123], v[72:75]
	v_mfma_f32_16x16x32_bf16 v[80:83], v[228:231], v[128:131], v[80:83]
	ds_read_b64_tr_b16 v[248:249], v174 offset:46176
	ds_read_b64_tr_b16 v[250:251], v174 offset:50784
	s_waitcnt lgkmcnt(8)
	v_mfma_f32_16x16x32_bf16 v[84:87], v[232:235], v[120:123], v[84:87]
	v_mfma_f32_16x16x32_bf16 v[20:23], v[232:235], v[128:131], v[20:23]
	ds_read_b64_tr_b16 v[228:229], v174 offset:46208
	ds_read_b64_tr_b16 v[230:231], v174 offset:50816
	s_waitcnt lgkmcnt(8)
	v_mfma_f32_16x16x32_bf16 v[28:31], v[236:239], v[124:127], v[28:31]
	v_mfma_f32_16x16x32_bf16 v[36:39], v[236:239], v[152:155], v[36:39]
	ds_read_b64_tr_b16 v[232:233], v174 offset:46240
	ds_read_b64_tr_b16 v[234:235], v174 offset:50848
	s_waitcnt lgkmcnt(8)
	v_mfma_f32_16x16x32_bf16 v[32:35], v[240:243], v[124:127], v[32:35]
	v_mfma_f32_16x16x32_bf16 v[44:47], v[240:243], v[152:155], v[44:47]
	ds_read_b64_tr_b16 v[236:237], v174 offset:46272
	ds_read_b64_tr_b16 v[238:239], v174 offset:50880
	s_waitcnt lgkmcnt(8)
	v_mfma_f32_16x16x32_bf16 v[40:43], v[244:247], v[124:127], v[40:43]
	v_mfma_f32_16x16x32_bf16 v[48:51], v[244:247], v[152:155], v[48:51]
	ds_read_b64_tr_b16 v[240:241], v174 offset:46304
	ds_read_b64_tr_b16 v[242:243], v174 offset:50912
	s_waitcnt lgkmcnt(8)
	v_mfma_f32_16x16x32_bf16 v[52:55], v[248:251], v[124:127], v[52:55]
	v_mfma_f32_16x16x32_bf16 v[60:63], v[248:251], v[152:155], v[60:63]
	ds_read_b128 v[244:247], v173 offset:0
	s_waitcnt lgkmcnt(7)
	v_mfma_f32_16x16x32_bf16 v[56:59], v[228:231], v[124:127], v[56:59]
	v_mfma_f32_16x16x32_bf16 v[68:71], v[228:231], v[152:155], v[68:71]
	ds_read_b128 v[248:251], v173 offset:64
	s_waitcnt lgkmcnt(6)
	v_mfma_f32_16x16x32_bf16 v[64:67], v[232:235], v[124:127], v[64:67]
	v_mfma_f32_16x16x32_bf16 v[76:79], v[232:235], v[152:155], v[76:79]
	ds_read_b128 v[228:231], v173 offset:4608
	s_waitcnt lgkmcnt(5)
	v_mfma_f32_16x16x32_bf16 v[72:75], v[236:239], v[124:127], v[72:75]
	v_mfma_f32_16x16x32_bf16 v[80:83], v[236:239], v[152:155], v[80:83]
	ds_read_b128 v[232:235], v173 offset:4672
	s_waitcnt lgkmcnt(4)
	v_mfma_f32_16x16x32_bf16 v[84:87], v[240:243], v[124:127], v[84:87]
	v_mfma_f32_16x16x32_bf16 v[20:23], v[240:243], v[152:155], v[20:23]
	ds_read_b128 v[236:239], v173 offset:9216
	s_waitcnt lgkmcnt(4)
	v_mfma_f32_16x16x32_bf16 v[88:91], v[244:247], v[4:7], v[156:159]
	ds_read_b128 v[240:243], v173 offset:9280
	s_waitcnt lgkmcnt(4)
	v_mfma_f32_16x16x32_bf16 v[88:91], v[248:251], v[8:11], v[88:91]
	ds_read_b128 v[244:247], v173 offset:13824
	s_waitcnt lgkmcnt(4)
	v_mfma_f32_16x16x32_bf16 v[92:95], v[228:231], v[4:7], v[160:163]
	ds_read_b128 v[248:251], v173 offset:13888
	s_waitcnt lgkmcnt(4)
	v_mfma_f32_16x16x32_bf16 v[92:95], v[232:235], v[8:11], v[92:95]
	ds_read_b128 v[228:231], v173 offset:128
	s_waitcnt lgkmcnt(4)
	v_mfma_f32_16x16x32_bf16 v[96:99], v[236:239], v[4:7], v[176:179]
	ds_read_b128 v[232:235], v173 offset:192
	s_waitcnt lgkmcnt(4)
	v_mfma_f32_16x16x32_bf16 v[96:99], v[240:243], v[8:11], v[96:99]
	ds_read_b128 v[236:239], v173 offset:4736
	s_waitcnt lgkmcnt(4)
	v_mfma_f32_16x16x32_bf16 v[100:103], v[244:247], v[4:7], v[180:183]
	ds_read_b128 v[240:243], v173 offset:4800
	s_waitcnt lgkmcnt(4)
	v_mfma_f32_16x16x32_bf16 v[100:103], v[248:251], v[8:11], v[100:103]
	ds_read_b128 v[244:247], v173 offset:9344
	s_waitcnt lgkmcnt(4)
	v_mfma_f32_16x16x32_bf16 v[104:107], v[228:231], v[12:15], v[204:207]
	ds_read_b128 v[248:251], v173 offset:9408
	s_waitcnt lgkmcnt(4)
	v_mfma_f32_16x16x32_bf16 v[104:107], v[232:235], v[16:19], v[104:107]
	ds_read_b128 v[228:231], v173 offset:13952
	s_waitcnt lgkmcnt(4)
	v_mfma_f32_16x16x32_bf16 v[108:111], v[236:239], v[12:15], v[208:211]
	ds_read_b128 v[232:235], v173 offset:14016
	s_waitcnt lgkmcnt(4)
	v_mfma_f32_16x16x32_bf16 v[108:111], v[240:243], v[16:19], v[108:111]
	s_waitcnt lgkmcnt(3)
	v_mfma_f32_16x16x32_bf16 v[112:115], v[244:247], v[12:15], v[184:187]
	s_waitcnt lgkmcnt(2)
	v_mfma_f32_16x16x32_bf16 v[112:115], v[248:251], v[16:19], v[112:115]
	s_waitcnt lgkmcnt(1)
	v_mfma_f32_16x16x32_bf16 v[116:119], v[228:231], v[12:15], v[188:191]
	s_waitcnt lgkmcnt(0)
	v_mfma_f32_16x16x32_bf16 v[116:119], v[232:235], v[16:19], v[116:119]
	v_max3_f32 v26, v88, v89, v90
	v_max3_f32 v26, v26, v91, v92
	v_max3_f32 v26, v26, v93, v94
	v_max3_f32 v26, v26, v95, v96
	v_max3_f32 v26, v26, v97, v98
	v_max3_f32 v26, v26, v99, v100
	v_max3_f32 v26, v26, v101, v102
	v_max_f32_e32 v26, v26, v103
	v_cmp_lt_f32_e32 vcc, s66, v26
	s_cbranch_vccz .Ld_nr_A_0
	v_mov_b32_e32 v27, v26
	s_nop 1
	v_permlane16_swap_b32_e32 v26, v27
	v_max_f32_e32 v26, v26, v27
	v_mov_b32_e32 v27, v26
	s_nop 1
	v_permlane32_swap_b32_e32 v26, v27
	v_max_f32_e32 v26, v26, v27
	v_cmp_lt_f32_e32 vcc, s66, v26
	s_nop 1
	v_cndmask_b32_e32 v2, 0, v26, vcc
	v_sub_f32_e32 v3, 0, v2
	v_min_f32_e32 v3, 0, v3
	v_exp_f32_e32 v3, v3
	v_sub_f32_e32 v24, v24, v2
	v_mul_f32_e32 v0, v0, v3
	v_mul_f32_e32 v28, v28, v3
	v_mul_f32_e32 v29, v29, v3
	v_mul_f32_e32 v30, v30, v3
	v_mul_f32_e32 v31, v31, v3
	v_mul_f32_e32 v32, v32, v3
	v_mul_f32_e32 v33, v33, v3
	v_mul_f32_e32 v34, v34, v3
	v_mul_f32_e32 v35, v35, v3
	v_mul_f32_e32 v40, v40, v3
	v_mul_f32_e32 v41, v41, v3
	v_mul_f32_e32 v42, v42, v3
	v_mul_f32_e32 v43, v43, v3
	v_mul_f32_e32 v52, v52, v3
	v_mul_f32_e32 v53, v53, v3
	v_mul_f32_e32 v54, v54, v3
	v_mul_f32_e32 v55, v55, v3
	v_mul_f32_e32 v56, v56, v3
	v_mul_f32_e32 v57, v57, v3
	v_mul_f32_e32 v58, v58, v3
	v_mul_f32_e32 v59, v59, v3
	v_mul_f32_e32 v64, v64, v3
	v_mul_f32_e32 v65, v65, v3
	v_mul_f32_e32 v66, v66, v3
	v_mul_f32_e32 v67, v67, v3
	v_mul_f32_e32 v72, v72, v3
	v_mul_f32_e32 v73, v73, v3
	v_mul_f32_e32 v74, v74, v3
	v_mul_f32_e32 v75, v75, v3
	v_mul_f32_e32 v84, v84, v3
	v_mul_f32_e32 v85, v85, v3
	v_mul_f32_e32 v86, v86, v3
	v_mul_f32_e32 v87, v87, v3
	v_sub_f32_e32 v88, v88, v2
	v_sub_f32_e32 v89, v89, v2
	v_sub_f32_e32 v90, v90, v2
	v_sub_f32_e32 v91, v91, v2
	v_sub_f32_e32 v92, v92, v2
	v_sub_f32_e32 v93, v93, v2
	v_sub_f32_e32 v94, v94, v2
	v_sub_f32_e32 v95, v95, v2
	v_sub_f32_e32 v96, v96, v2
	v_sub_f32_e32 v97, v97, v2
	v_sub_f32_e32 v98, v98, v2
	v_sub_f32_e32 v99, v99, v2
	v_sub_f32_e32 v100, v100, v2
	v_sub_f32_e32 v101, v101, v2
	v_sub_f32_e32 v102, v102, v2
	v_sub_f32_e32 v103, v103, v2

.Ld_nr_A_1:
	v_exp_f32_e32 v104, v104
	v_exp_f32_e32 v105, v105
	v_exp_f32_e32 v106, v106
	v_exp_f32_e32 v107, v107
	v_exp_f32_e32 v108, v108
	v_exp_f32_e32 v109, v109
	v_exp_f32_e32 v110, v110
	v_exp_f32_e32 v111, v111
	v_exp_f32_e32 v112, v112
	v_exp_f32_e32 v113, v113
	v_exp_f32_e32 v114, v114
	v_exp_f32_e32 v115, v115
	v_exp_f32_e32 v116, v116
	v_exp_f32_e32 v117, v117
	v_exp_f32_e32 v118, v118
	v_exp_f32_e32 v119, v119
	s_nop 0
	v_add_f32_e32 v26, v104, v105
	v_add_f32_e32 v26, v26, v106
	v_add_f32_e32 v26, v26, v107
	v_add_f32_e32 v26, v26, v108
	v_add_f32_e32 v26, v26, v109
	v_add_f32_e32 v26, v26, v110
	v_add_f32_e32 v26, v26, v111
	v_add_f32_e32 v26, v26, v112
	v_add_f32_e32 v26, v26, v113
	v_add_f32_e32 v26, v26, v114
	v_add_f32_e32 v26, v26, v115
	v_add_f32_e32 v26, v26, v116
	v_add_f32_e32 v26, v26, v117
	v_add_f32_e32 v26, v26, v118
	v_add_f32_e32 v26, v26, v119
	v_add_f32_e32 v151, v151, v26
	v_cvt_pk_bf16_f32 v128, v104, v105
	v_cvt_pk_bf16_f32 v129, v106, v107
	v_cvt_pk_bf16_f32 v130, v108, v109
	v_cvt_pk_bf16_f32 v131, v110, v111
	v_cvt_pk_bf16_f32 v152, v112, v113
	v_cvt_pk_bf16_f32 v153, v114, v115
	v_cvt_pk_bf16_f32 v154, v116, v117
	v_cvt_pk_bf16_f32 v155, v118, v119
	v_add_f32_e32 v165, 0x42800000, v165
	v_mov_b32_e32 v156, v165
	v_add_f32_e32 v157, 0x3f800000, v165
	v_add_f32_e32 v158, 0x40000000, v165
	v_add_f32_e32 v159, 0x40400000, v165
	v_add_f32_e32 v160, 0x41800000, v165
	v_add_f32_e32 v161, 0x41880000, v165
	v_add_f32_e32 v162, 0x41900000, v165
	v_add_f32_e32 v163, 0x41980000, v165
	v_add_f32_e32 v176, 0x42000000, v165
	v_add_f32_e32 v177, 0x42040000, v165
	v_add_f32_e32 v178, 0x42080000, v165
	v_add_f32_e32 v179, 0x420c0000, v165
	v_add_f32_e32 v180, 0x42400000, v165
	v_add_f32_e32 v181, 0x42440000, v165
	v_add_f32_e32 v182, 0x42480000, v165
	v_add_f32_e32 v183, 0x424c0000, v165
	v_fma_f32 v204, -v150, |v156|, v25
	v_fma_f32 v205, -v150, |v157|, v25
	v_fma_f32 v206, -v150, |v158|, v25
	v_fma_f32 v207, -v150, |v159|, v25
	v_fma_f32 v208, -v150, |v160|, v25
	v_fma_f32 v209, -v150, |v161|, v25
	v_fma_f32 v210, -v150, |v162|, v25
	v_fma_f32 v211, -v150, |v163|, v25
	v_fma_f32 v184, -v150, |v176|, v25
	v_fma_f32 v185, -v150, |v177|, v25
	v_fma_f32 v186, -v150, |v178|, v25
	v_fma_f32 v187, -v150, |v179|, v25
	v_fma_f32 v188, -v150, |v180|, v25
	v_fma_f32 v189, -v150, |v181|, v25
	v_fma_f32 v190, -v150, |v182|, v25
	v_fma_f32 v191, -v150, |v183|, v25
	v_fma_f32 v156, -v150, |v156|, v24
	v_fma_f32 v157, -v150, |v157|, v24
	v_fma_f32 v158, -v150, |v158|, v24
	v_fma_f32 v159, -v150, |v159|, v24
	v_fma_f32 v160, -v150, |v160|, v24
	v_fma_f32 v161, -v150, |v161|, v24
	v_fma_f32 v162, -v150, |v162|, v24
	v_fma_f32 v163, -v150, |v163|, v24
	v_fma_f32 v176, -v150, |v176|, v24
	v_fma_f32 v177, -v150, |v177|, v24
	v_fma_f32 v178, -v150, |v178|, v24
	v_fma_f32 v179, -v150, |v179|, v24
	v_fma_f32 v180, -v150, |v180|, v24
	v_fma_f32 v181, -v150, |v181|, v24
	v_fma_f32 v182, -v150, |v182|, v24
	v_fma_f32 v183, -v150, |v183|, v24
	s_waitcnt vmcnt(0)
	ds_write_b128 v175, v[212:215]
	ds_write_b128 v175, v[216:219] offset:9216
	ds_write_b128 v164, v[220:223] offset:36864
	ds_write_b128 v164, v[224:227] offset:46080
	s_mov_b32 s31, s38
	s_mov_b32 s38, s39
	s_add_i32 s39, s39, 0x4800
	s_cmp_lg_u32 s39, 0xd800
	s_cselect_b32 s39, s39, 0
	s_mov_b32 s66, 0x41000000
	s_add_i32 s5, s5, 1
	s_min_u32 s8, s5, 62
	s_add_i32 s8, s8, 1
	s_mul_i32 s30, s8, 0xf8000
	s_waitcnt lgkmcnt(0)
	s_barrier
	s_cmp_lt_u32 s5, 64
	s_cbranch_scc1 .Ld_loopA
	v_add_u32_e32 v174, s31, v168
	ds_read_b64_tr_b16 v[228:229], v174 offset:36864
	ds_read_b64_tr_b16 v[230:231], v174 offset:41472
	ds_read_b64_tr_b16 v[232:233], v174 offset:36896
	ds_read_b64_tr_b16 v[234:235], v174 offset:41504
	ds_read_b64_tr_b16 v[236:237], v174 offset:36928
	ds_read_b64_tr_b16 v[238:239], v174 offset:41536
	ds_read_b64_tr_b16 v[240:241], v174 offset:36960
	ds_read_b64_tr_b16 v[242:243], v174 offset:41568
	ds_read_b64_tr_b16 v[244:245], v174 offset:36992
	ds_read_b64_tr_b16 v[246:247], v174 offset:41600
	s_waitcnt lgkmcnt(8)
	v_mfma_f32_16x16x32_bf16 v[28:31], v[228:231], v[120:123], v[28:31]
	v_mfma_f32_16x16x32_bf16 v[36:39], v[228:231], v[128:131], v[36:39]
	ds_read_b64_tr_b16 v[248:249], v174 offset:37024
	ds_read_b64_tr_b16 v[250:251], v174 offset:41632
	s_waitcnt lgkmcnt(8)
	v_mfma_f32_16x16x32_bf16 v[32:35], v[232:235], v[120:123], v[32:35]
	v_mfma_f32_16x16x32_bf16 v[44:47], v[232:235], v[128:131], v[44:47]
	ds_read_b64_tr_b16 v[228:229], v174 offset:37056
	ds_read_b64_tr_b16 v[230:231], v174 offset:41664
	s_waitcnt lgkmcnt(8)
	v_mfma_f32_16x16x32_bf16 v[40:43], v[236:239], v[120:123], v[40:43]
	v_mfma_f32_16x16x32_bf16 v[48:51], v[236:239], v[128:131], v[48:51]
	ds_read_b64_tr_b16 v[232:233], v174 offset:37088
	ds_read_b64_tr_b16 v[234:235], v174 offset:41696
	s_waitcnt lgkmcnt(8)
	v_mfma_f32_16x16x32_bf16 v[52:55], v[240:243], v[120:123], v[52:55]
	v_mfma_f32_16x16x32_bf16 v[60:63], v[240:243], v[128:131], v[60:63]
	ds_read_b64_tr_b16 v[236:237], v174 offset:46080
	ds_read_b64_tr_b16 v[238:239], v174 offset:50688
	s_waitcnt lgkmcnt(8)
	v_mfma_f32_16x16x32_bf16 v[56:59], v[244:247], v[120:123], v[56:59]
	v_mfma_f32_16x16x32_bf16 v[68:71], v[244:247], v[128:131], v[68:71]
	ds_read_b64_tr_b16 v[240:241], v174 offset:46112
	ds_read_b64_tr_b16 v[242:243], v174 offset:50720
	s_waitcnt lgkmcnt(8)
	v_mfma_f32_16x16x32_bf16 v[64:67], v[248:251], v[120:123], v[64:67]
	v_mfma_f32_16x16x32_bf16 v[76:79], v[248:251], v[128:131], v[76:79]
	ds_read_b64_tr_b16 v[244:245], v174 offset:46144
	ds_read_b64_tr_b16 v[246:247], v174 offset:50752
	s_waitcnt lgkmcnt(8)
	v_mfma_f32_16x16x32_bf16 v[72:75], v[228:231], v[120:123], v[72:75]
	v_mfma_f32_16x16x32_bf16 v[80:83], v[228:231], v[128:131], v[80:83]
	ds_read_b64_tr_b16 v[248:249], v174 offset:46176
	ds_read_b64_tr_b16 v[250:251], v174 offset:50784
	s_waitcnt lgkmcnt(8)
	v_mfma_f32_16x16x32_bf16 v[84:87], v[232:235], v[120:123], v[84:87]
	v_mfma_f32_16x16x32_bf16 v[20:23], v[232:235], v[128:131], v[20:23]
	ds_read_b64_tr_b16 v[228:229], v174 offset:46208
	ds_read_b64_tr_b16 v[230:231], v174 offset:50816
	s_waitcnt lgkmcnt(8)
	v_mfma_f32_16x16x32_bf16 v[28:31], v[236:239], v[124:127], v[28:31]
	v_mfma_f32_16x16x32_bf16 v[36:39], v[236:239], v[152:155], v[36:39]
	ds_read_b64_tr_b16 v[232:233], v174 offset:46240
	ds_read_b64_tr_b16 v[234:235], v174 offset:50848
	s_waitcnt lgkmcnt(8)
	v_mfma_f32_16x16x32_bf16 v[32:35], v[240:243], v[124:127], v[32:35]
	v_mfma_f32_16x16x32_bf16 v[44:47], v[240:243], v[152:155], v[44:47]
	ds_read_b64_tr_b16 v[236:237], v174 offset:46272
	ds_read_b64_tr_b16 v[238:239], v174 offset:50880
	s_waitcnt lgkmcnt(8)
	v_mfma_f32_16x16x32_bf16 v[40:43], v[244:247], v[124:127], v[40:43]
	v_mfma_f32_16x16x32_bf16 v[48:51], v[244:247], v[152:155], v[48:51]
	ds_read_b64_tr_b16 v[240:241], v174 offset:46304
	ds_read_b64_tr_b16 v[242:243], v174 offset:50912
	s_waitcnt lgkmcnt(8)
	v_mfma_f32_16x16x32_bf16 v[52:55], v[248:251], v[124:127], v[52:55]
	v_mfma_f32_16x16x32_bf16 v[60:63], v[248:251], v[152:155], v[60:63]
	s_waitcnt lgkmcnt(6)
	v_mfma_f32_16x16x32_bf16 v[56:59], v[228:231], v[124:127], v[56:59]
	v_mfma_f32_16x16x32_bf16 v[68:71], v[228:231], v[152:155], v[68:71]
	s_waitcnt lgkmcnt(4)
	v_mfma_f32_16x16x32_bf16 v[64:67], v[232:235], v[124:127], v[64:67]
	v_mfma_f32_16x16x32_bf16 v[76:79], v[232:235], v[152:155], v[76:79]
	s_waitcnt lgkmcnt(2)
	v_mfma_f32_16x16x32_bf16 v[72:75], v[236:239], v[124:127], v[72:75]
	v_mfma_f32_16x16x32_bf16 v[80:83], v[236:239], v[152:155], v[80:83]
	s_waitcnt lgkmcnt(0)
	v_mfma_f32_16x16x32_bf16 v[84:87], v[240:243], v[124:127], v[84:87]
	v_mfma_f32_16x16x32_bf16 v[20:23], v[240:243], v[152:155], v[20:23]

.Lb_loopB:
	s_and_b32 s8, s20, 1
	s_mul_i32 s32, s8, 10240
	s_xor_b32 s8, s8, 1
	s_mul_i32 s8, s8, 10240
	v_add_u32_e32 v71, s32, v75
	v_add_u32_e32 v73, s8, v120
	v_add_u32_e32 v72, s42, v119
	v_add_u32_e32 v74, s51, v120
	s_mov_b32 s19, 0
	s_mov_b32 s18, s30
	v_lshl_add_u64 v[208:209], v[112:113], 0, s[18:19]
	v_lshl_add_u64 v[212:213], v[114:115], 0, s[18:19]
	global_load_dwordx4 v[208:211], v[208:209], off
	global_load_dwordx4 v[212:215], v[212:213], off
	ds_read_b128 v[216:219], v71 offset:0
	ds_read_b128 v[220:223], v71 offset:64
	ds_read_b128 v[224:227], v71 offset:2560
	ds_read_b128 v[228:231], v71 offset:2624
	ds_read_b128 v[232:235], v71 offset:5120
	ds_read_b128 v[236:239], v71 offset:5184
	v_max3_f32 v67, v88, v89, v90
	v_max3_f32 v67, v67, v91, v92
	v_max3_f32 v67, v67, v93, v94
	v_max3_f32 v67, v67, v95, v96
	v_max3_f32 v67, v67, v97, v98
	v_max3_f32 v67, v67, v99, v100
	v_max3_f32 v67, v67, v101, v102
	v_max_f32_e32 v67, v67, v103
	v_cmp_lt_f32_e32 vcc, s66, v67
	s_cbranch_vccz .Lb_nr_B_0
	v_mov_b32_e32 v68, v67
	s_nop 1
	v_permlane16_swap_b32_e32 v67, v68
	v_max_f32_e32 v67, v67, v68
	v_mov_b32_e32 v68, v67
	s_nop 1
	v_permlane32_swap_b32_e32 v67, v68
	v_max_f32_e32 v67, v67, v68
	v_cmp_lt_f32_e32 vcc, s66, v67
	s_nop 1
	v_cndmask_b32_e32 v69, 0, v67, vcc
	v_sub_f32_e32 v70, 0, v69
	v_min_f32_e32 v70, 0, v70
	v_exp_f32_e32 v70, v70
	v_sub_f32_e32 v48, v48, v69
	v_sub_f32_e32 v49, v49, v69
	v_sub_f32_e32 v50, v50, v69
	v_sub_f32_e32 v51, v51, v69
	v_mul_f32_e32 v80, v80, v70
	v_mul_f32_e32 v34, v34, v70
	v_mul_f32_e32 v35, v35, v70
	v_mul_f32_e32 v36, v36, v70
	v_mul_f32_e32 v37, v37, v70
	v_mul_f32_e32 v42, v42, v70
	v_mul_f32_e32 v43, v43, v70
	v_mul_f32_e32 v44, v44, v70
	v_mul_f32_e32 v45, v45, v70
	v_mul_f32_e32 v56, v56, v70
	v_mul_f32_e32 v57, v57, v70
	v_mul_f32_e32 v58, v58, v70
	v_mul_f32_e32 v59, v59, v70
	v_mul_f32_e32 v60, v60, v70
	v_mul_f32_e32 v61, v61, v70
	v_mul_f32_e32 v62, v62, v70
	v_mul_f32_e32 v63, v63, v70
	v_sub_f32_e32 v88, v88, v69
	v_sub_f32_e32 v89, v89, v69
	v_sub_f32_e32 v90, v90, v69
	v_sub_f32_e32 v91, v91, v69
	v_sub_f32_e32 v92, v92, v69
	v_sub_f32_e32 v93, v93, v69
	v_sub_f32_e32 v94, v94, v69
	v_sub_f32_e32 v95, v95, v69
	v_sub_f32_e32 v96, v96, v69
	v_sub_f32_e32 v97, v97, v69
	v_sub_f32_e32 v98, v98, v69
	v_sub_f32_e32 v99, v99, v69
	v_sub_f32_e32 v100, v100, v69
	v_sub_f32_e32 v101, v101, v69
	v_sub_f32_e32 v102, v102, v69
	v_sub_f32_e32 v103, v103, v69
.Lb_nr_B_0:
	v_exp_f32_e32 v88, v88
	v_exp_f32_e32 v89, v89
	v_exp_f32_e32 v90, v90
	v_exp_f32_e32 v91, v91
	v_exp_f32_e32 v92, v92
	v_exp_f32_e32 v93, v93
	v_exp_f32_e32 v94, v94
	v_exp_f32_e32 v95, v95
	v_exp_f32_e32 v96, v96
	v_exp_f32_e32 v97, v97
	v_exp_f32_e32 v98, v98
	v_exp_f32_e32 v99, v99
	v_exp_f32_e32 v100, v100
	v_exp_f32_e32 v101, v101
	v_exp_f32_e32 v102, v102
	v_exp_f32_e32 v103, v103
	s_nop 0
	v_add_f32_e32 v67, v88, v89
	v_add_f32_e32 v67, v67, v90
	v_add_f32_e32 v67, v67, v91
	v_add_f32_e32 v67, v67, v92
	v_add_f32_e32 v67, v67, v93
	v_add_f32_e32 v67, v67, v94
	v_add_f32_e32 v67, v67, v95
	v_add_f32_e32 v67, v67, v96
	v_add_f32_e32 v67, v67, v97
	v_add_f32_e32 v67, v67, v98
	v_add_f32_e32 v67, v67, v99
	v_add_f32_e32 v67, v67, v100
	v_add_f32_e32 v67, v67, v101
	v_add_f32_e32 v67, v67, v102
	v_add_f32_e32 v67, v67, v103
	v_add_f32_e32 v80, v80, v67
	v_cvt_pk_bf16_f32 v180, v88, v89
	v_cvt_pk_bf16_f32 v181, v90, v91
	v_cvt_pk_bf16_f32 v182, v92, v93
	v_cvt_pk_bf16_f32 v183, v94, v95
	v_cvt_pk_bf16_f32 v188, v96, v97
	v_cvt_pk_bf16_f32 v189, v98, v99
	v_cvt_pk_bf16_f32 v190, v100, v101
	v_cvt_pk_bf16_f32 v191, v102, v103
	v_max3_f32 v67, v104, v105, v106
	v_max3_f32 v67, v67, v107, v168
	v_max3_f32 v67, v67, v169, v170
	v_max3_f32 v67, v67, v171, v172
	v_max3_f32 v67, v67, v173, v174
	v_max3_f32 v67, v67, v175, v176
	v_max3_f32 v67, v67, v177, v178
	v_max_f32_e32 v67, v67, v179
	v_cmp_lt_f32_e32 vcc, s66, v67
	s_cbranch_vccz .Lb_nr_B_1
	v_mov_b32_e32 v68, v67
	s_nop 1
	v_permlane16_swap_b32_e32 v67, v68
	v_max_f32_e32 v67, v67, v68
	v_mov_b32_e32 v68, v67
	s_nop 1
	v_permlane32_swap_b32_e32 v67, v68
	v_max_f32_e32 v67, v67, v68
	v_cmp_lt_f32_e32 vcc, s66, v67
	s_nop 1
	v_cndmask_b32_e32 v69, 0, v67, vcc
	v_sub_f32_e32 v70, 0, v69
	v_min_f32_e32 v70, 0, v70
	v_exp_f32_e32 v70, v70
	v_sub_f32_e32 v52, v52, v69
	v_sub_f32_e32 v53, v53, v69
	v_sub_f32_e32 v54, v54, v69
	v_sub_f32_e32 v55, v55, v69
	v_mul_f32_e32 v64, v64, v70
	v_mul_f32_e32 v20, v20, v70
	v_mul_f32_e32 v21, v21, v70
	v_mul_f32_e32 v22, v22, v70
	v_mul_f32_e32 v23, v23, v70
	v_mul_f32_e32 v24, v24, v70
	v_mul_f32_e32 v25, v25, v70
	v_mul_f32_e32 v26, v26, v70
	v_mul_f32_e32 v27, v27, v70
	v_mul_f32_e32 v38, v38, v70
	v_mul_f32_e32 v39, v39, v70
	v_mul_f32_e32 v40, v40, v70
	v_mul_f32_e32 v41, v41, v70
	v_mul_f32_e32 v28, v28, v70
	v_mul_f32_e32 v29, v29, v70
	v_mul_f32_e32 v30, v30, v70
	v_mul_f32_e32 v31, v31, v70
	v_sub_f32_e32 v104, v104, v69
	v_sub_f32_e32 v105, v105, v69
	v_sub_f32_e32 v106, v106, v69
	v_sub_f32_e32 v107, v107, v69
	v_sub_f32_e32 v168, v168, v69
	v_sub_f32_e32 v169, v169, v69
	v_sub_f32_e32 v170, v170, v69
	v_sub_f32_e32 v171, v171, v69
	v_sub_f32_e32 v172, v172, v69
	v_sub_f32_e32 v173, v173, v69
	v_sub_f32_e32 v174, v174, v69
	v_sub_f32_e32 v175, v175, v69
	v_sub_f32_e32 v176, v176, v69
	v_sub_f32_e32 v177, v177, v69
	v_sub_f32_e32 v178, v178, v69
	v_sub_f32_e32 v179, v179, v69
.Lb_nr_B_1:
	v_exp_f32_e32 v104, v104
	v_exp_f32_e32 v105, v105
	v_exp_f32_e32 v106, v106
	v_exp_f32_e32 v107, v107
	v_exp_f32_e32 v168, v168
	v_exp_f32_e32 v169, v169
	v_exp_f32_e32 v170, v170
	v_exp_f32_e32 v171, v171
	v_exp_f32_e32 v172, v172
	v_exp_f32_e32 v173, v173
	v_exp_f32_e32 v174, v174
	v_exp_f32_e32 v175, v175
	v_exp_f32_e32 v176, v176
	v_exp_f32_e32 v177, v177
	v_exp_f32_e32 v178, v178
	v_exp_f32_e32 v179, v179
	s_nop 0
	v_add_f32_e32 v67, v104, v105
	v_add_f32_e32 v67, v67, v106
	v_add_f32_e32 v67, v67, v107
	v_add_f32_e32 v67, v67, v168
	v_add_f32_e32 v67, v67, v169
	v_add_f32_e32 v67, v67, v170
	v_add_f32_e32 v67, v67, v171
	v_add_f32_e32 v67, v67, v172
	v_add_f32_e32 v67, v67, v173
	v_add_f32_e32 v67, v67, v174
	v_add_f32_e32 v67, v67, v175
	v_add_f32_e32 v67, v67, v176
	v_add_f32_e32 v67, v67, v177
	v_add_f32_e32 v67, v67, v178
	v_add_f32_e32 v67, v67, v179
	v_add_f32_e32 v64, v64, v67
	v_cvt_pk_bf16_f32 v184, v104, v105
	v_cvt_pk_bf16_f32 v185, v106, v107
	v_cvt_pk_bf16_f32 v186, v168, v169
	v_cvt_pk_bf16_f32 v187, v170, v171
	v_cvt_pk_bf16_f32 v204, v172, v173
	v_cvt_pk_bf16_f32 v205, v174, v175
	v_cvt_pk_bf16_f32 v206, v176, v177
	v_cvt_pk_bf16_f32 v207, v178, v179
	ds_read_b128 v[240:243], v71 offset:7680
	s_waitcnt lgkmcnt(6)
	v_mfma_f32_16x16x32_bf16 v[88:91], v[216:219], v[16:19], v[48:51]
	v_mfma_f32_16x16x32_bf16 v[104:107], v[216:219], v[12:15], v[52:55]
	ds_read_b128 v[244:247], v71 offset:7744
	s_waitcnt lgkmcnt(6)
	v_mfma_f32_16x16x32_bf16 v[88:91], v[220:223], v[8:11], v[88:91]
	v_mfma_f32_16x16x32_bf16 v[104:107], v[220:223], v[4:7], v[104:107]
	ds_read_b64_tr_b16 v[248:249], v72 offset:20480
	ds_read_b64_tr_b16 v[250:251], v72 offset:23040
	s_waitcnt lgkmcnt(7)
	v_mfma_f32_16x16x32_bf16 v[92:95], v[224:227], v[16:19], v[48:51]
	v_mfma_f32_16x16x32_bf16 v[168:171], v[224:227], v[12:15], v[52:55]
	ds_read_b64_tr_b16 v[216:217], v72 offset:20512
	ds_read_b64_tr_b16 v[218:219], v72 offset:23072
	s_waitcnt lgkmcnt(8)
	v_mfma_f32_16x16x32_bf16 v[92:95], v[228:231], v[8:11], v[92:95]
	v_mfma_f32_16x16x32_bf16 v[168:171], v[228:231], v[4:7], v[168:171]
	ds_read_b64_tr_b16 v[220:221], v72 offset:20544
	ds_read_b64_tr_b16 v[222:223], v72 offset:23104
	s_waitcnt lgkmcnt(9)
	v_mfma_f32_16x16x32_bf16 v[96:99], v[232:235], v[16:19], v[48:51]
	v_mfma_f32_16x16x32_bf16 v[172:175], v[232:235], v[12:15], v[52:55]
	ds_read_b64_tr_b16 v[224:225], v72 offset:20576
	ds_read_b64_tr_b16 v[226:227], v72 offset:23136
	s_waitcnt lgkmcnt(10)
	v_mfma_f32_16x16x32_bf16 v[96:99], v[236:239], v[8:11], v[96:99]
	v_mfma_f32_16x16x32_bf16 v[172:175], v[236:239], v[4:7], v[172:175]
	ds_read_b64_tr_b16 v[228:229], v72 offset:25600
	ds_read_b64_tr_b16 v[230:231], v72 offset:28160
	s_waitcnt lgkmcnt(11)
	v_mfma_f32_16x16x32_bf16 v[100:103], v[240:243], v[16:19], v[48:51]
	v_mfma_f32_16x16x32_bf16 v[176:179], v[240:243], v[12:15], v[52:55]
	ds_read_b64_tr_b16 v[232:233], v72 offset:25632
	ds_read_b64_tr_b16 v[234:235], v72 offset:28192
	s_waitcnt lgkmcnt(12)
	v_mfma_f32_16x16x32_bf16 v[100:103], v[244:247], v[8:11], v[100:103]
	v_mfma_f32_16x16x32_bf16 v[176:179], v[244:247], v[4:7], v[176:179]
	ds_read_b64_tr_b16 v[236:237], v72 offset:25664
	ds_read_b64_tr_b16 v[238:239], v72 offset:28224
	s_waitcnt lgkmcnt(12)
	v_mfma_f32_16x16x32_bf16 v[34:37], v[248:251], v[180:183], v[34:37]
	v_mfma_f32_16x16x32_bf16 v[20:23], v[248:251], v[184:187], v[20:23]
	ds_read_b64_tr_b16 v[240:241], v72 offset:25696
	ds_read_b64_tr_b16 v[242:243], v72 offset:28256
	s_waitcnt lgkmcnt(12)
	v_mfma_f32_16x16x32_bf16 v[42:45], v[216:219], v[180:183], v[42:45]
	v_mfma_f32_16x16x32_bf16 v[24:27], v[216:219], v[184:187], v[24:27]
	s_waitcnt lgkmcnt(10)
	v_mfma_f32_16x16x32_bf16 v[56:59], v[220:223], v[180:183], v[56:59]
	v_mfma_f32_16x16x32_bf16 v[38:41], v[220:223], v[184:187], v[38:41]
	s_waitcnt lgkmcnt(8)
	v_mfma_f32_16x16x32_bf16 v[60:63], v[224:227], v[180:183], v[60:63]
	v_mfma_f32_16x16x32_bf16 v[28:31], v[224:227], v[184:187], v[28:31]
	s_waitcnt lgkmcnt(6)
	v_mfma_f32_16x16x32_bf16 v[34:37], v[228:231], v[188:191], v[34:37]
	v_mfma_f32_16x16x32_bf16 v[20:23], v[228:231], v[204:207], v[20:23]
	s_waitcnt lgkmcnt(4)
	v_mfma_f32_16x16x32_bf16 v[42:45], v[232:235], v[188:191], v[42:45]
	v_mfma_f32_16x16x32_bf16 v[24:27], v[232:235], v[204:207], v[24:27]
	s_waitcnt lgkmcnt(2)
	v_mfma_f32_16x16x32_bf16 v[56:59], v[236:239], v[188:191], v[56:59]
	v_mfma_f32_16x16x32_bf16 v[38:41], v[236:239], v[204:207], v[38:41]
	s_waitcnt lgkmcnt(0)
	v_mfma_f32_16x16x32_bf16 v[60:63], v[240:243], v[188:191], v[60:63]
	v_mfma_f32_16x16x32_bf16 v[28:31], v[240:243], v[204:207], v[28:31]
	s_waitcnt vmcnt(0)
	ds_write_b128 v73, v[208:211]
	ds_write_b128 v74, v[212:215] offset:20480
	s_mov_b32 s42, s43
	s_mov_b32 s43, s51
	s_add_i32 s51, s51, 10240
	s_cmp_lg_u32 s51, 30720
	s_cselect_b32 s51, s51, 0
	s_mov_b32 s66, 0xff800000
	s_cmp_ge_u32 s20, 1
	s_cselect_b32 s66, 0x41000000, s66
	s_add_i32 s20, s20, 1
	s_min_u32 s8, s20, 62
	s_add_i32 s8, s8, 1
	s_mul_i32 s30, s8, 0xf8000
	s_waitcnt lgkmcnt(0)
	s_barrier
	s_cmp_lt_u32 s20, 64
	s_cbranch_scc1 .Lb_loopB
	v_add_u32_e32 v72, s42, v119
	ds_read_b64_tr_b16 v[216:217], v72 offset:20480
	ds_read_b64_tr_b16 v[218:219], v72 offset:23040
	ds_read_b64_tr_b16 v[220:221], v72 offset:20512
	ds_read_b64_tr_b16 v[222:223], v72 offset:23072
	ds_read_b64_tr_b16 v[224:225], v72 offset:20544
	ds_read_b64_tr_b16 v[226:227], v72 offset:23104
	ds_read_b64_tr_b16 v[228:229], v72 offset:20576
	ds_read_b64_tr_b16 v[230:231], v72 offset:23136
	ds_read_b64_tr_b16 v[232:233], v72 offset:25600
	ds_read_b64_tr_b16 v[234:235], v72 offset:28160
	ds_read_b64_tr_b16 v[236:237], v72 offset:25632
	ds_read_b64_tr_b16 v[238:239], v72 offset:28192
	v_max3_f32 v67, v88, v89, v90
	v_max3_f32 v67, v67, v91, v92
	v_max3_f32 v67, v67, v93, v94
	v_max3_f32 v67, v67, v95, v96
	v_max3_f32 v67, v67, v97, v98
	v_max3_f32 v67, v67, v99, v100
	v_max3_f32 v67, v67, v101, v102
	v_max_f32_e32 v67, v67, v103
	v_cmp_lt_f32_e32 vcc, s66, v67
	s_cbranch_vccz .Lb_nr_Bt_0
	v_mov_b32_e32 v68, v67
	s_nop 1
	v_permlane16_swap_b32_e32 v67, v68
	v_max_f32_e32 v67, v67, v68
	v_mov_b32_e32 v68, v67
	s_nop 1
	v_permlane32_swap_b32_e32 v67, v68
	v_max_f32_e32 v67, v67, v68
	v_cmp_lt_f32_e32 vcc, s66, v67
	s_nop 1
	v_cndmask_b32_e32 v69, 0, v67, vcc
	v_sub_f32_e32 v70, 0, v69
	v_min_f32_e32 v70, 0, v70
	v_exp_f32_e32 v70, v70
	v_sub_f32_e32 v48, v48, v69
	v_sub_f32_e32 v49, v49, v69
	v_sub_f32_e32 v50, v50, v69
	v_sub_f32_e32 v51, v51, v69
	v_mul_f32_e32 v80, v80, v70
	v_mul_f32_e32 v34, v34, v70
	v_mul_f32_e32 v35, v35, v70
	v_mul_f32_e32 v36, v36, v70
	v_mul_f32_e32 v37, v37, v70
	v_mul_f32_e32 v42, v42, v70
	v_mul_f32_e32 v43, v43, v70
	v_mul_f32_e32 v44, v44, v70
	v_mul_f32_e32 v45, v45, v70
	v_mul_f32_e32 v56, v56, v70
	v_mul_f32_e32 v57, v57, v70
	v_mul_f32_e32 v58, v58, v70
	v_mul_f32_e32 v59, v59, v70
	v_mul_f32_e32 v60, v60, v70
	v_mul_f32_e32 v61, v61, v70
	v_mul_f32_e32 v62, v62, v70
	v_mul_f32_e32 v63, v63, v70
	v_sub_f32_e32 v88, v88, v69
	v_sub_f32_e32 v89, v89, v69
	v_sub_f32_e32 v90, v90, v69
	v_sub_f32_e32 v91, v91, v69
	v_sub_f32_e32 v92, v92, v69
	v_sub_f32_e32 v93, v93, v69
	v_sub_f32_e32 v94, v94, v69
	v_sub_f32_e32 v95, v95, v69
	v_sub_f32_e32 v96, v96, v69
	v_sub_f32_e32 v97, v97, v69
	v_sub_f32_e32 v98, v98, v69
	v_sub_f32_e32 v99, v99, v69
	v_sub_f32_e32 v100, v100, v69
	v_sub_f32_e32 v101, v101, v69
	v_sub_f32_e32 v102, v102, v69
	v_sub_f32_e32 v103, v103, v69

.Lb_loopA:
	s_and_b32 s8, s20, 1
	s_mul_i32 s32, s8, 10240
	s_xor_b32 s8, s8, 1
	s_mul_i32 s8, s8, 10240
	v_add_u32_e32 v71, s32, v75
	v_add_u32_e32 v73, s8, v120
	v_add_u32_e32 v72, s42, v119
	v_add_u32_e32 v74, s51, v120
	s_mov_b32 s19, 0
	s_mov_b32 s18, s30
	v_lshl_add_u64 v[208:209], v[112:113], 0, s[18:19]
	v_lshl_add_u64 v[212:213], v[114:115], 0, s[18:19]
	global_load_dwordx4 v[208:211], v[208:209], off
	global_load_dwordx4 v[212:215], v[212:213], off
	ds_read_b64_tr_b16 v[216:217], v72 offset:20480
	ds_read_b64_tr_b16 v[218:219], v72 offset:23040
	ds_read_b64_tr_b16 v[220:221], v72 offset:20512
	ds_read_b64_tr_b16 v[222:223], v72 offset:23072
	ds_read_b64_tr_b16 v[224:225], v72 offset:20544
	ds_read_b64_tr_b16 v[226:227], v72 offset:23104
	ds_read_b64_tr_b16 v[228:229], v72 offset:20576
	ds_read_b64_tr_b16 v[230:231], v72 offset:23136
	ds_read_b64_tr_b16 v[232:233], v72 offset:25600
	ds_read_b64_tr_b16 v[234:235], v72 offset:28160
	ds_read_b64_tr_b16 v[236:237], v72 offset:25632
	ds_read_b64_tr_b16 v[238:239], v72 offset:28192
	ds_read_b64_tr_b16 v[240:241], v72 offset:25664
	ds_read_b64_tr_b16 v[242:243], v72 offset:28224
	s_waitcnt lgkmcnt(12)
	v_mfma_f32_16x16x32_bf16 v[34:37], v[216:219], v[180:183], v[34:37]
	v_mfma_f32_16x16x32_bf16 v[20:23], v[216:219], v[184:187], v[20:23]
	ds_read_b64_tr_b16 v[244:245], v72 offset:25696
	ds_read_b64_tr_b16 v[246:247], v72 offset:28256
	s_waitcnt lgkmcnt(12)
	v_mfma_f32_16x16x32_bf16 v[42:45], v[220:223], v[180:183], v[42:45]
	v_mfma_f32_16x16x32_bf16 v[24:27], v[220:223], v[184:187], v[24:27]
	ds_read_b128 v[248:251], v71 offset:0
	s_waitcnt lgkmcnt(11)
	v_mfma_f32_16x16x32_bf16 v[56:59], v[224:227], v[180:183], v[56:59]
	v_mfma_f32_16x16x32_bf16 v[38:41], v[224:227], v[184:187], v[38:41]
	ds_read_b128 v[216:219], v71 offset:64
	s_waitcnt lgkmcnt(10)
	v_mfma_f32_16x16x32_bf16 v[60:63], v[228:231], v[180:183], v[60:63]
	v_mfma_f32_16x16x32_bf16 v[28:31], v[228:231], v[184:187], v[28:31]
	ds_read_b128 v[220:223], v71 offset:2560
	s_waitcnt lgkmcnt(9)
	v_mfma_f32_16x16x32_bf16 v[34:37], v[232:235], v[188:191], v[34:37]
	v_mfma_f32_16x16x32_bf16 v[20:23], v[232:235], v[204:207], v[20:23]
	ds_read_b128 v[224:227], v71 offset:2624
	s_waitcnt lgkmcnt(8)
	v_mfma_f32_16x16x32_bf16 v[42:45], v[236:239], v[188:191], v[42:45]
	v_mfma_f32_16x16x32_bf16 v[24:27], v[236:239], v[204:207], v[24:27]
	ds_read_b128 v[228:231], v71 offset:5120
	s_waitcnt lgkmcnt(7)
	v_mfma_f32_16x16x32_bf16 v[56:59], v[240:243], v[188:191], v[56:59]
	v_mfma_f32_16x16x32_bf16 v[38:41], v[240:243], v[204:207], v[38:41]
	ds_read_b128 v[232:235], v71 offset:5184
	s_waitcnt lgkmcnt(6)
	v_mfma_f32_16x16x32_bf16 v[60:63], v[244:247], v[188:191], v[60:63]
	v_mfma_f32_16x16x32_bf16 v[28:31], v[244:247], v[204:207], v[28:31]
	ds_read_b128 v[236:239], v71 offset:7680
	s_waitcnt lgkmcnt(6)
	v_mfma_f32_16x16x32_bf16 v[88:91], v[248:251], v[16:19], v[48:51]
	v_mfma_f32_16x16x32_bf16 v[104:107], v[248:251], v[12:15], v[52:55]
	ds_read_b128 v[240:243], v71 offset:7744
	s_waitcnt lgkmcnt(6)
	v_mfma_f32_16x16x32_bf16 v[88:91], v[216:219], v[8:11], v[88:91]
	v_mfma_f32_16x16x32_bf16 v[104:107], v[216:219], v[4:7], v[104:107]
	s_waitcnt lgkmcnt(5)
	v_mfma_f32_16x16x32_bf16 v[92:95], v[220:223], v[16:19], v[48:51]
	v_mfma_f32_16x16x32_bf16 v[168:171], v[220:223], v[12:15], v[52:55]
	s_waitcnt lgkmcnt(4)
	v_mfma_f32_16x16x32_bf16 v[92:95], v[224:227], v[8:11], v[92:95]
	v_mfma_f32_16x16x32_bf16 v[168:171], v[224:227], v[4:7], v[168:171]
	s_waitcnt lgkmcnt(3)
	v_mfma_f32_16x16x32_bf16 v[96:99], v[228:231], v[16:19], v[48:51]
	v_mfma_f32_16x16x32_bf16 v[172:175], v[228:231], v[12:15], v[52:55]
	s_waitcnt lgkmcnt(2)
	v_mfma_f32_16x16x32_bf16 v[96:99], v[232:235], v[8:11], v[96:99]
	v_mfma_f32_16x16x32_bf16 v[172:175], v[232:235], v[4:7], v[172:175]
	s_waitcnt lgkmcnt(1)
	v_mfma_f32_16x16x32_bf16 v[100:103], v[236:239], v[16:19], v[48:51]
	v_mfma_f32_16x16x32_bf16 v[176:179], v[236:239], v[12:15], v[52:55]
	s_waitcnt lgkmcnt(0)
	v_mfma_f32_16x16x32_bf16 v[100:103], v[240:243], v[8:11], v[100:103]
	v_mfma_f32_16x16x32_bf16 v[176:179], v[240:243], v[4:7], v[176:179]
	s_mov_b32 s42, s43
	s_mov_b32 s43, s51
	s_add_i32 s51, s51, 10240
	s_cmp_lg_u32 s51, 30720
	s_cselect_b32 s51, s51, 0
	s_min_u32 s8, s20, 61
	s_add_i32 s8, s8, 2
	s_mul_i32 s30, s8, 0xf8000
	s_nop 1
	v_max3_f32 v67, v88, v89, v90
	v_max3_f32 v67, v67, v91, v92
	v_max3_f32 v67, v67, v93, v94
	v_max3_f32 v67, v67, v95, v96
	v_max3_f32 v67, v67, v97, v98
	v_max3_f32 v67, v67, v99, v100
	v_max3_f32 v67, v67, v101, v102
	v_max_f32_e32 v67, v67, v103
	v_cmp_lt_f32_e32 vcc, s66, v67
	s_cbranch_vccz .Lb_nr_A_0
	v_mov_b32_e32 v68, v67
	s_nop 1
	v_permlane16_swap_b32_e32 v67, v68
	v_max_f32_e32 v67, v67, v68
	v_mov_b32_e32 v68, v67
	s_nop 1
	v_permlane32_swap_b32_e32 v67, v68
	v_max_f32_e32 v67, v67, v68
	v_cmp_lt_f32_e32 vcc, s66, v67
	s_nop 1
	v_cndmask_b32_e32 v69, 0, v67, vcc
	v_sub_f32_e32 v70, 0, v69
	v_min_f32_e32 v70, 0, v70
	v_exp_f32_e32 v70, v70
	v_sub_f32_e32 v48, v48, v69
	v_sub_f32_e32 v49, v49, v69
	v_sub_f32_e32 v50, v50, v69
	v_sub_f32_e32 v51, v51, v69
	v_mul_f32_e32 v80, v80, v70
	v_mul_f32_e32 v34, v34, v70
	v_mul_f32_e32 v35, v35, v70
	v_mul_f32_e32 v36, v36, v70
	v_mul_f32_e32 v37, v37, v70
	v_mul_f32_e32 v42, v42, v70
	v_mul_f32_e32 v43, v43, v70
	v_mul_f32_e32 v44, v44, v70
	v_mul_f32_e32 v45, v45, v70
	v_mul_f32_e32 v56, v56, v70
	v_mul_f32_e32 v57, v57, v70
	v_mul_f32_e32 v58, v58, v70
	v_mul_f32_e32 v59, v59, v70
	v_mul_f32_e32 v60, v60, v70
	v_mul_f32_e32 v61, v61, v70
	v_mul_f32_e32 v62, v62, v70
	v_mul_f32_e32 v63, v63, v70
	v_sub_f32_e32 v88, v88, v69
	v_sub_f32_e32 v89, v89, v69
	v_sub_f32_e32 v90, v90, v69
	v_sub_f32_e32 v91, v91, v69
	v_sub_f32_e32 v92, v92, v69
	v_sub_f32_e32 v93, v93, v69
	v_sub_f32_e32 v94, v94, v69
	v_sub_f32_e32 v95, v95, v69
	v_sub_f32_e32 v96, v96, v69
	v_sub_f32_e32 v97, v97, v69
	v_sub_f32_e32 v98, v98, v69
	v_sub_f32_e32 v99, v99, v69
	v_sub_f32_e32 v100, v100, v69
	v_sub_f32_e32 v101, v101, v69
	v_sub_f32_e32 v102, v102, v69
	v_sub_f32_e32 v103, v103, v69
